# ph3 MLA-up GEMM skips the zero-weight K ranges per column tile (per-tile K bounds)
# speedup vs baseline: 1.0178x; 1.0043x over previous
; template <class Epi, class Sched>
; __device__ __forceinline__ void gemm_phase(LAS unsigned char* lds, const Gemm g, const Sched& S, const Epi& E, int wv) {
;     ...
;         const bool has_next = S.next(ui + 1, nxt);
;         const char* nA = has_next ? (const char*)g.A + (size_t)nxt.pm * tstepA + (size_t)nxt.ak * 2 : cA; const char* nB = has_next ? (const char*)g.Bt + (size_t)nxt.pn * tstepB : cB;
;     ...
; #pragma unroll
;         for (int a = 0; a < 2; ++a)
; #pragma unroll
;             for (int b = 0; b < 2; ++b)
; #pragma unroll
;                 for (int m = 0; m < 4; ++m)
; #pragma unroll
;                     for (int n = 0; n < 2; ++n) acc[a][b][m][n] = (f32x4){0.f, 0.f, 0.f, 0.f};
;         cur = nxt; cA = nA; cB = nB; ++ui;
.LBB0_200:
	s_ashr_i32 s71, s70, 31
	s_lshl_b64 s[0:1], s[70:71], 19
	s_add_u32 s72, s47, s0
	s_addc_u32 s73, s48, s1
	s_and_b64 s[0:1], s[2:3], exec
	s_cselect_b32 s10, s73, s77
	s_cselect_b32 s11, s72, s76
	s_ashr_i32 s69, s68, 31
	s_lshl_b64 s[0:1], s[68:69], 19
	s_add_u32 s74, s49, s0
	s_addc_u32 s75, s50, s1
	s_and_b64 s[0:1], s[2:3], exec
	s_cselect_b32 s21, s75, s79
	s_cselect_b32 s31, s74, s78
	s_add_u32 s76, s76, 0x40080
	s_addc_u32 s77, s77, 0
	s_add_u32 s34, s78, 0x100
	v_mov_b32_e32 v2, 0
	s_addc_u32 s35, s79, 0
	s_mov_b32 s56, -2
	v_mov_b64_e32 v[2:3], 0
	v_mov_b64_e32 v[4:5], 0
	v_mov_b64_e32 v[6:7], 0
	v_mov_b64_e32 v[8:9], 0
	v_mov_b64_e32 v[10:11], 0
	v_mov_b64_e32 v[12:13], 0
	v_mov_b64_e32 v[14:15], 0
	v_mov_b64_e32 v[16:17], 0
	v_mov_b64_e32 v[18:19], 0
	v_mov_b64_e32 v[20:21], 0
	v_mov_b64_e32 v[22:23], 0
	v_mov_b64_e32 v[24:25], 0
	v_mov_b64_e32 v[26:27], 0
	v_mov_b64_e32 v[28:29], 0
	v_mov_b64_e32 v[30:31], 0
	v_mov_b64_e32 v[32:33], 0
	v_mov_b64_e32 v[34:35], 0
	v_mov_b64_e32 v[36:37], 0
	v_mov_b64_e32 v[38:39], 0
	v_mov_b64_e32 v[40:41], 0
	v_mov_b64_e32 v[42:43], 0
	v_mov_b64_e32 v[44:45], 0
	v_mov_b64_e32 v[46:47], 0
	v_mov_b64_e32 v[48:49], 0
	v_mov_b64_e32 v[50:51], 0
	v_mov_b64_e32 v[52:53], 0
	v_mov_b64_e32 v[54:55], 0
	v_mov_b64_e32 v[56:57], 0
	v_mov_b64_e32 v[58:59], 0
	v_mov_b64_e32 v[60:61], 0
	v_mov_b64_e32 v[62:63], 0
	v_mov_b64_e32 v[64:65], 0
	v_mov_b64_e32 v[66:67], 0
	v_mov_b64_e32 v[68:69], 0
	v_mov_b64_e32 v[70:71], 0
	v_mov_b64_e32 v[72:73], 0
	v_mov_b64_e32 v[74:75], 0
	v_mov_b64_e32 v[76:77], 0
	v_mov_b64_e32 v[78:79], 0
	v_mov_b64_e32 v[80:81], 0
	v_mov_b64_e32 v[82:83], 0
	v_mov_b64_e32 v[84:85], 0
	v_mov_b64_e32 v[86:87], 0
	v_mov_b64_e32 v[88:89], 0
	v_mov_b64_e32 v[90:91], 0
	v_mov_b64_e32 v[92:93], 0
	v_mov_b64_e32 v[94:95], 0
	v_mov_b64_e32 v[96:97], 0
	v_mov_b64_e32 v[98:99], 0
	v_mov_b64_e32 v[100:101], 0
	v_mov_b64_e32 v[102:103], 0
	v_mov_b64_e32 v[104:105], 0
	v_mov_b64_e32 v[106:107], 0
	v_mov_b64_e32 v[108:109], 0
	v_mov_b64_e32 v[110:111], 0
	v_mov_b64_e32 v[112:113], 0
	v_mov_b64_e32 v[114:115], 0
	v_mov_b64_e32 v[116:117], 0
	v_mov_b64_e32 v[118:119], 0
	v_mov_b64_e32 v[120:121], 0
	v_mov_b64_e32 v[122:123], 0
	v_mov_b64_e32 v[124:125], 0
	v_mov_b64_e32 v[126:127], 0
	v_mov_b64_e32 v[128:129], 0

; template <class Epi, class Sched>
; __device__ __forceinline__ void gemm_phase(LAS unsigned char* lds, const Gemm g, const Sched& S, const Epi& E, int wv) {
;     ...
;         const bool has_next = S.next(ui + 1, nxt);
;         const char* nA = has_next ? (const char*)g.A + (size_t)nxt.pm * tstepA + (size_t)nxt.ak * 2 : cA; const char* nB = has_next ? (const char*)g.Bt + (size_t)nxt.pn * tstepB : cB;
;     ...
; #pragma unroll
;         for (int a = 0; a < 2; ++a)
; #pragma unroll
;             for (int b = 0; b < 2; ++b)
; #pragma unroll
;                 for (int m = 0; m < 4; ++m)
; #pragma unroll
;                     for (int n = 0; n < 2; ++n) acc[a][b][m][n] = (f32x4){0.f, 0.f, 0.f, 0.f};
;         cur = nxt; cA = nA; cB = nB; ++ui;
.LBB0_224:
	s_ashr_i32 s75, s74, 31
	s_lshl_b64 s[0:1], s[74:75], 17
	s_add_u32 s76, s48, s0
	s_addc_u32 s77, s49, s1
	s_and_b64 s[0:1], s[2:3], exec
	s_cselect_b32 s75, s77, s71
	s_cselect_b32 s31, s76, s70
	s_ashr_i32 s73, s72, 31
	s_lshl_b64 s[0:1], s[72:73], 17
	s_add_u32 s78, s50, s0
	s_addc_u32 s79, s60, s1
	s_and_b64 s[0:1], s[2:3], exec
	v_mov_b32_e32 v2, 0
	s_cselect_b32 s73, s79, s69
	s_cselect_b32 s34, s78, s68
	s_mov_b32 s35, 0
	s_mov_b64 s[80:81], -1
	s_mov_b64 s[82:83], 0
	v_mov_b64_e32 v[2:3], 0
	v_mov_b64_e32 v[4:5], 0
	v_mov_b64_e32 v[6:7], 0
	v_mov_b64_e32 v[8:9], 0
	v_mov_b64_e32 v[10:11], 0
	v_mov_b64_e32 v[12:13], 0
	v_mov_b64_e32 v[14:15], 0
	v_mov_b64_e32 v[16:17], 0
	v_mov_b64_e32 v[18:19], 0
	v_mov_b64_e32 v[20:21], 0
	v_mov_b64_e32 v[22:23], 0
	v_mov_b64_e32 v[24:25], 0
	v_mov_b64_e32 v[26:27], 0
	v_mov_b64_e32 v[28:29], 0
	v_mov_b64_e32 v[30:31], 0
	v_mov_b64_e32 v[32:33], 0
	v_mov_b64_e32 v[34:35], 0
	v_mov_b64_e32 v[36:37], 0
	v_mov_b64_e32 v[38:39], 0
	v_mov_b64_e32 v[40:41], 0
	v_mov_b64_e32 v[42:43], 0
	v_mov_b64_e32 v[44:45], 0
	v_mov_b64_e32 v[46:47], 0
	v_mov_b64_e32 v[48:49], 0
	v_mov_b64_e32 v[50:51], 0
	v_mov_b64_e32 v[52:53], 0
	v_mov_b64_e32 v[54:55], 0
	v_mov_b64_e32 v[56:57], 0
	v_mov_b64_e32 v[58:59], 0
	v_mov_b64_e32 v[60:61], 0
	v_mov_b64_e32 v[62:63], 0
	v_mov_b64_e32 v[64:65], 0
	v_mov_b64_e32 v[66:67], 0
	v_mov_b64_e32 v[68:69], 0
	v_mov_b64_e32 v[70:71], 0
	v_mov_b64_e32 v[72:73], 0
	v_mov_b64_e32 v[74:75], 0
	v_mov_b64_e32 v[76:77], 0
	v_mov_b64_e32 v[78:79], 0
	v_mov_b64_e32 v[80:81], 0
	v_mov_b64_e32 v[82:83], 0
	v_mov_b64_e32 v[84:85], 0
	v_mov_b64_e32 v[86:87], 0
	v_mov_b64_e32 v[88:89], 0
	v_mov_b64_e32 v[90:91], 0
	v_mov_b64_e32 v[92:93], 0
	v_mov_b64_e32 v[94:95], 0
	v_mov_b64_e32 v[96:97], 0
	v_mov_b64_e32 v[98:99], 0
	v_mov_b64_e32 v[100:101], 0
	v_mov_b64_e32 v[102:103], 0
	v_mov_b64_e32 v[104:105], 0
	v_mov_b64_e32 v[106:107], 0
	v_mov_b64_e32 v[108:109], 0
	v_mov_b64_e32 v[110:111], 0
	v_mov_b64_e32 v[112:113], 0
	v_mov_b64_e32 v[114:115], 0
	v_mov_b64_e32 v[116:117], 0
	v_mov_b64_e32 v[118:119], 0
	v_mov_b64_e32 v[120:121], 0
	v_mov_b64_e32 v[122:123], 0
	v_mov_b64_e32 v[124:125], 0
	v_mov_b64_e32 v[126:127], 0
	v_mov_b64_e32 v[128:129], 0

; template <class Epi, class Sched>
; __device__ __forceinline__ void gemm_phase(LAS unsigned char* lds, const Gemm g, const Sched& S, const Epi& E, int wv) {
;     ...
;         const bool has_next = S.next(ui + 1, nxt);
;         const char* nA = has_next ? (const char*)g.A + (size_t)nxt.pm * tstepA + (size_t)nxt.ak * 2 : cA; const char* nB = has_next ? (const char*)g.Bt + (size_t)nxt.pn * tstepB : cB;
;     ...
; #pragma unroll
;         for (int a = 0; a < 2; ++a)
; #pragma unroll
;             for (int b = 0; b < 2; ++b)
; #pragma unroll
;                 for (int m = 0; m < 4; ++m)
; #pragma unroll
;                     for (int n = 0; n < 2; ++n) acc[a][b][m][n] = (f32x4){0.f, 0.f, 0.f, 0.f};
;         cur = nxt; cA = nA; cB = nB; ++ui;
.LBB0_303:
	s_ashr_i32 s69, s68, 31
	s_lshl_b64 s[0:1], s[68:69], 19
	s_add_u32 s70, s47, s0
	s_addc_u32 s71, s48, s1
	s_and_b64 s[0:1], s[2:3], exec
	s_cselect_b32 s5, s71, s75
	s_cselect_b32 s10, s70, s74
	s_ashr_i32 s67, s66, 31
	s_lshl_b64 s[0:1], s[66:67], 19
	s_add_u32 s72, s49, s0
	s_addc_u32 s73, s50, s1
	s_and_b64 s[0:1], s[2:3], exec
	s_cselect_b32 s11, s73, s79
	s_cselect_b32 s21, s72, s78
	s_add_u32 s74, s74, 0x40080
	s_addc_u32 s75, s75, 0
	s_add_u32 s31, s78, 0x100
	v_mov_b32_e32 v2, 0
	s_addc_u32 s34, s79, 0
	s_mov_b32 s35, -2
	v_mov_b64_e32 v[2:3], 0
	v_mov_b64_e32 v[4:5], 0
	v_mov_b64_e32 v[6:7], 0
	v_mov_b64_e32 v[8:9], 0
	v_mov_b64_e32 v[10:11], 0
	v_mov_b64_e32 v[12:13], 0
	v_mov_b64_e32 v[14:15], 0
	v_mov_b64_e32 v[16:17], 0
	v_mov_b64_e32 v[18:19], 0
	v_mov_b64_e32 v[20:21], 0
	v_mov_b64_e32 v[22:23], 0
	v_mov_b64_e32 v[24:25], 0
	v_mov_b64_e32 v[26:27], 0
	v_mov_b64_e32 v[28:29], 0
	v_mov_b64_e32 v[30:31], 0
	v_mov_b64_e32 v[32:33], 0
	v_mov_b64_e32 v[34:35], 0
	v_mov_b64_e32 v[36:37], 0
	v_mov_b64_e32 v[38:39], 0
	v_mov_b64_e32 v[40:41], 0
	v_mov_b64_e32 v[42:43], 0
	v_mov_b64_e32 v[44:45], 0
	v_mov_b64_e32 v[46:47], 0
	v_mov_b64_e32 v[48:49], 0
	v_mov_b64_e32 v[50:51], 0
	v_mov_b64_e32 v[52:53], 0
	v_mov_b64_e32 v[54:55], 0
	v_mov_b64_e32 v[56:57], 0
	v_mov_b64_e32 v[58:59], 0
	v_mov_b64_e32 v[60:61], 0
	v_mov_b64_e32 v[62:63], 0
	v_mov_b64_e32 v[64:65], 0
	v_mov_b64_e32 v[66:67], 0
	v_mov_b64_e32 v[68:69], 0
	v_mov_b64_e32 v[70:71], 0
	v_mov_b64_e32 v[72:73], 0
	v_mov_b64_e32 v[74:75], 0
	v_mov_b64_e32 v[76:77], 0
	v_mov_b64_e32 v[78:79], 0
	v_mov_b64_e32 v[80:81], 0
	v_mov_b64_e32 v[82:83], 0
	v_mov_b64_e32 v[84:85], 0
	v_mov_b64_e32 v[86:87], 0
	v_mov_b64_e32 v[88:89], 0
	v_mov_b64_e32 v[90:91], 0
	v_mov_b64_e32 v[92:93], 0
	v_mov_b64_e32 v[94:95], 0
	v_mov_b64_e32 v[96:97], 0
	v_mov_b64_e32 v[98:99], 0
	v_mov_b64_e32 v[100:101], 0
	v_mov_b64_e32 v[102:103], 0
	v_mov_b64_e32 v[104:105], 0
	v_mov_b64_e32 v[106:107], 0
	v_mov_b64_e32 v[108:109], 0
	v_mov_b64_e32 v[110:111], 0
	v_mov_b64_e32 v[112:113], 0
	v_mov_b64_e32 v[114:115], 0
	v_mov_b64_e32 v[116:117], 0
	v_mov_b64_e32 v[118:119], 0
	v_mov_b64_e32 v[120:121], 0
	v_mov_b64_e32 v[122:123], 0
	v_mov_b64_e32 v[124:125], 0
	v_mov_b64_e32 v[126:127], 0
	v_mov_b64_e32 v[128:129], 0

; __device__ __forceinline__ unsigned cvtpk(float lo, float hi) { f32x2 v = {lo, hi}; bf16x2_t b = __builtin_convertvector(v, bf16x2_t); return __builtin_bit_cast(unsigned, b); }
; #define VFRAG(off) ({ const s16x4 lo_ = vtr(vb + (off)); const s16x4 hi_ = vtr(vb + (off) + 512); (bf16x8){lo_[0], lo_[1], lo_[2], lo_[3], hi_[0], hi_[1], hi_[2], hi_[3]}; })
; __device__ __forceinline__ void softmax_pv(WaveAttn& st, f32x16 s, LAS const unsigned char* vb, int lane) {
;     ...
;     const float mn = st.m;
;     float ps = 0.f;
; #pragma unroll
;     for (int r = 0; r < 16; ++r) { s[r] = __builtin_amdgcn_exp2f(s[r] - mn); ps += s[r]; }
;     st.l += ps;
;     u32x4 p0, p1;
;     p0.x = cvtpk(s[0], s[1]); p0.y = cvtpk(s[2], s[3]); p0.z = cvtpk(s[4], s[5]); p0.w = cvtpk(s[6], s[7]);
;     p1.x = cvtpk(s[8], s[9]); p1.y = cvtpk(s[10], s[11]); p1.z = cvtpk(s[12], s[13]); p1.w = cvtpk(s[14], s[15]);
;     const bf16x8 pb0 = __builtin_bit_cast(bf16x8, p0), pb1 = __builtin_bit_cast(bf16x8, p1);
;     ...
;     { const bf16x8 v00 = VFRAG(0), v01 = VFRAG(1024), v10 = VFRAG(2048), v11 = VFRAG(2048 + 1024);
;       st.o0 = __builtin_amdgcn_mfma_f32_32x32x16_bf16(v00, pb0, st.o0, 0, 0, 0);
;       st.o0 = __builtin_amdgcn_mfma_f32_32x32x16_bf16(v01, pb1, st.o0, 0, 0, 0);
;       st.o1 = __builtin_amdgcn_mfma_f32_32x32x16_bf16(v10, pb0, st.o1, 0, 0, 0);
;       st.o1 = __builtin_amdgcn_mfma_f32_32x32x16_bf16(v11, pb1, st.o1, 0, 0, 0); }
.LBB0_491:
	v_add_f32_e32 v81, v82, v81
	v_add_f32_e32 v81, v83, v81
	v_add_f32_e32 v81, v84, v81
	v_add_f32_e32 v81, v85, v81
	v_add_f32_e32 v81, v86, v81
	v_sub_f32_e32 v82, v96, v249
	v_add_f32_e32 v81, v87, v81
	v_exp_f32_e32 v87, v82
	v_sub_f32_e32 v82, v97, v249
	v_add_f32_e32 v81, v88, v81
	v_exp_f32_e32 v88, v82
	v_sub_f32_e32 v82, v98, v249
	v_add_f32_e32 v81, v89, v81
	v_exp_f32_e32 v89, v82
	v_sub_f32_e32 v82, v99, v249
	v_exp_f32_e32 v98, v82
	v_sub_f32_e32 v82, v100, v249
	v_add_f32_e32 v81, v90, v81
	v_exp_f32_e32 v99, v82
	v_sub_f32_e32 v82, v101, v249
	v_add_f32_e32 v81, v91, v81
	v_exp_f32_e32 v100, v82
	v_sub_f32_e32 v82, v102, v249
	v_add_f32_e32 v81, v93, v81
	v_sub_f32_e32 v0, v0, v249
	v_exp_f32_e32 v101, v82
	v_sub_f32_e32 v82, v103, v249
	v_add_f32_e32 v81, v94, v81
	v_exp_f32_e32 v0, v0
	v_sub_f32_e32 v15, v15, v249
	v_exp_f32_e32 v102, v82
	v_sub_f32_e32 v82, v104, v249
	v_add_f32_e32 v81, v95, v81
	v_exp_f32_e32 v15, v15
	v_exp_f32_e32 v103, v82
	v_sub_f32_e32 v82, v105, v249
	v_add_f32_e32 v81, v110, v81
	v_exp_f32_e32 v104, v82
	v_sub_f32_e32 v82, v106, v249
	v_add_f32_e32 v81, v92, v81
	v_exp_f32_e32 v105, v82
	v_sub_f32_e32 v82, v107, v249
	v_add_f32_e32 v220, v220, v81
	v_add_f32_e32 v81, 0, v0
	v_exp_f32_e32 v106, v82
	ds_read_b64_tr_b16 v[82:83], v80
	ds_read_b64_tr_b16 v[84:85], v80 offset:512
	v_add_f32_e32 v81, v15, v81
	v_add_f32_e32 v81, v87, v81
	v_add_f32_e32 v81, v88, v81
	v_sub_f32_e32 v86, v108, v249
	v_add_f32_e32 v81, v89, v81
	v_exp_f32_e32 v107, v86
	v_sub_f32_e32 v94, v109, v249
	v_cvt_pk_bf16_f32 v86, v0, v15
	v_cvt_pk_bf16_f32 v87, v87, v88
	v_cvt_pk_bf16_f32 v88, v89, v98
	v_cvt_pk_bf16_f32 v89, v99, v100
	ds_read_b64_tr_b16 v[90:91], v80 offset:1024
	ds_read_b64_tr_b16 v[92:93], v80 offset:1536
	s_waitcnt lgkmcnt(2)
	v_mfma_f32_32x32x16_bf16 v[32:47], v[82:85], v[86:89], v[32:47]
	v_exp_f32_e32 v0, v94
	ds_read_b64_tr_b16 v[94:95], v80 offset:2048
	ds_read_b64_tr_b16 v[96:97], v80 offset:2560
	v_cvt_pk_bf16_f32 v82, v101, v102
	v_cvt_pk_bf16_f32 v83, v103, v104
	v_cvt_pk_bf16_f32 v84, v105, v106
	v_cvt_pk_bf16_f32 v85, v107, v0
	v_add_f32_e32 v15, v98, v81
	s_waitcnt lgkmcnt(0)
	v_mfma_f32_32x32x16_bf16 v[16:31], v[94:97], v[86:89], v[16:31]
	v_add_f32_e32 v15, v99, v15
	v_add_f32_e32 v15, v100, v15
	v_add_f32_e32 v15, v101, v15
	v_add_f32_e32 v15, v102, v15
	v_add_f32_e32 v15, v103, v15
	v_add_f32_e32 v15, v104, v15
	v_add_f32_e32 v15, v105, v15
	v_mfma_f32_32x32x16_bf16 v[32:47], v[90:93], v[82:85], v[32:47]
	ds_read_b64_tr_b16 v[90:91], v80 offset:3072
	ds_read_b64_tr_b16 v[92:93], v80 offset:3584
	v_add_f32_e32 v15, v106, v15
	v_add_f32_e32 v15, v107, v15
	s_and_b64 s[0:1], exec, s[4:5]
	v_add_f32_e32 v0, v0, v15
	v_mov_b64_e32 v[174:175], v[8:9]
	v_mov_b64_e32 v[170:171], v[12:13]
	s_waitcnt lgkmcnt(0)
	v_mfma_f32_32x32x16_bf16 v[16:31], v[90:93], v[82:85], v[16:31]
	v_mov_b64_e32 v[82:83], v[4:5]
	v_mov_b64_e32 v[166:167], v[146:147]
	s_or_b64 s[78:79], s[0:1], s[78:79]
	v_add_u32_e32 v206, 1, v206
	v_add_f32_e32 v193, v193, v0
	v_add_u32_e32 v204, 64, v204
	v_add_u32_e32 v223, 1, v223
	v_mov_b64_e32 v[80:81], v[2:3]
	v_mov_b64_e32 v[172:173], v[6:7]
	v_mov_b64_e32 v[168:169], v[10:11]
	v_mov_b64_e32 v[164:165], v[144:145]
	s_andn2_b64 exec, exec, s[78:79]
	s_cbranch_execz .LBB0_498

; #define LAS __attribute__((address_space(3)))
; __device__ __forceinline__ float xhalf_max(float v) { float a = v, b = v; xhalf_swap(a, b); return fmaxf(a, b); }
; __device__ __forceinline__ void softmax_pv(WaveAttn& st, f32x16 s, LAS const unsigned char* vb, int lane) {
;     float mx = s[0];
; #pragma unroll
;     for (int r = 1; r < 16; ++r) mx = fmaxf(mx, s[r]);
;     mx = xhalf_max(mx);
;     if (__builtin_amdgcn_ballot_w64(mx > st.m + 8.0f) != 0ull) {
;         const float mn = fmaxf(st.m, mx);
;         const float alpha = __builtin_amdgcn_exp2f(st.m - mn);
;         st.m = mn; st.l *= alpha;
; #pragma unroll
;         for (int r = 0; r < 16; ++r) { st.o0[r] *= alpha; st.o1[r] *= alpha; }
;     }
; __device__ __forceinline__ f32x16 qk4(const bf16x8 (&kf)[4], const bf16x8 (&q)[4]) {
;     f32x16 s;
; #pragma unroll
;     for (int r = 0; r < 16; ++r) s[r] = 0.f;
; #pragma unroll
;     for (int ds = 0; ds < 4; ++ds) s = __builtin_amdgcn_mfma_f32_32x32x16_bf16(kf[ds], q[ds], s, 0, 0, 0);
;     return s;
; }
.LBB0_494:
	s_or_b64 exec, exec, s[6:7]
	v_mfma_f32_32x32x16_bf16 v[96:111], v[80:83], v[120:123], 0
	v_cmp_ge_u32_e32 vcc, v206, v221
	v_cmp_lt_u32_e64 s[6:7], v206, v231
	v_min_i32_e32 v0, 7, v223
	v_mov_b32_e32 v15, 0xe0
	s_and_b64 vcc, vcc, s[6:7]
	v_lshl_add_u32 v0, v0, 5, v15
	v_cndmask_b32_e32 v0, v228, v0, vcc
	v_mfma_f32_32x32x16_bf16 v[80:95], v[80:83], v[136:139], 0
	v_lshl_add_u32 v250, v0, 2, v216
	v_add_u32_e32 v0, v250, v233
	v_cmp_ge_u32_e32 vcc, v206, v222
	v_cmp_lt_u32_e64 s[6:7], v206, v232
	v_min_i32_e32 v15, 9, v223
	s_and_b64 vcc, vcc, s[6:7]
	v_lshl_add_u32 v15, v15, 5, v229
	v_mfma_f32_32x32x16_bf16 v[96:111], v[172:175], v[112:115], v[96:111]
	v_cndmask_b32_e32 v15, v228, v15, vcc
	v_lshl_add_u32 v205, v15, 2, v216
	v_add_u32_e32 v15, v250, v234
	v_mfma_f32_32x32x16_bf16 v[80:95], v[172:175], v[128:131], v[80:95]
	v_mfma_f32_32x32x16_bf16 v[96:111], v[168:171], v[116:119], v[96:111]
	v_mfma_f32_32x32x16_bf16 v[80:95], v[168:171], v[132:135], v[80:95]
	v_mfma_f32_32x32x16_bf16 v[96:111], v[164:167], v[124:127], v[96:111]
	v_mfma_f32_32x32x16_bf16 v[80:95], v[164:167], v[140:143], v[80:95]
	ds_read_b32 v164, v0
	ds_read_b32 v165, v15
	v_add_u32_e32 v0, v205, v233
	v_add_u32_e32 v15, v205, v234
	ds_read_b32 v0, v0
	ds_read_b32 v15, v15
	s_waitcnt lgkmcnt(3)
	s_nop 3
	v_fmac_f32_e32 v164, 0x3e38aa3b, v96
	v_add_u32_e32 v96, v250, v235
	ds_read_b32 v166, v96
	s_waitcnt lgkmcnt(3)
	v_fmac_f32_e32 v165, 0x3e38aa3b, v97
	v_add_u32_e32 v97, v250, v236
	ds_read_b32 v167, v97
	v_add_u32_e32 v96, v205, v235
	s_waitcnt lgkmcnt(1)
	v_fmac_f32_e32 v166, 0x3e38aa3b, v98
	v_add_u32_e32 v97, v205, v236
	v_add_u32_e32 v98, v250, v237
	ds_read_b32 v96, v96
	ds_read_b32 v97, v97
	ds_read_b32 v168, v98
	s_waitcnt lgkmcnt(3)
	v_fmac_f32_e32 v167, 0x3e38aa3b, v99
	v_add_u32_e32 v99, v250, v238
	ds_read_b32 v169, v99
	v_add_u32_e32 v98, v205, v237
	s_waitcnt lgkmcnt(1)
	v_fmac_f32_e32 v168, 0x3e38aa3b, v100
	v_add_u32_e32 v99, v205, v238
	v_add_u32_e32 v100, v250, v239
	ds_read_b32 v98, v98
	ds_read_b32 v99, v99
	ds_read_b32 v170, v100
	s_waitcnt lgkmcnt(3)
	v_fmac_f32_e32 v169, 0x3e38aa3b, v101
	v_add_u32_e32 v101, v250, v240
	ds_read_b32 v171, v101
	v_add_u32_e32 v100, v205, v239
	s_waitcnt lgkmcnt(1)
	v_fmac_f32_e32 v170, 0x3e38aa3b, v102
	v_add_u32_e32 v101, v205, v240
	v_add_u32_e32 v102, v250, v241
	ds_read_b32 v100, v100
	ds_read_b32 v101, v101
	ds_read_b32 v172, v102
	s_waitcnt lgkmcnt(3)
	v_fmac_f32_e32 v171, 0x3e38aa3b, v103
	v_add_u32_e32 v103, v250, v242
	ds_read_b32 v173, v103
	v_add_u32_e32 v102, v205, v241
	s_waitcnt lgkmcnt(1)
	v_fmac_f32_e32 v172, 0x3e38aa3b, v104
	v_add_u32_e32 v103, v205, v242
	v_add_u32_e32 v104, v250, v243
	ds_read_b32 v102, v102
	ds_read_b32 v103, v103
	ds_read_b32 v174, v104
	s_waitcnt lgkmcnt(3)
	v_fmac_f32_e32 v173, 0x3e38aa3b, v105
	v_add_u32_e32 v105, v250, v244
	ds_read_b32 v175, v105
	v_add_u32_e32 v104, v205, v243
	s_waitcnt lgkmcnt(1)
	v_fmac_f32_e32 v174, 0x3e38aa3b, v106
	v_add_u32_e32 v105, v205, v244
	v_add_u32_e32 v106, v250, v245
	ds_read_b32 v104, v104
	ds_read_b32 v105, v105
	ds_read_b32 v251, v106
	s_waitcnt lgkmcnt(3)
	v_fmac_f32_e32 v175, 0x3e38aa3b, v107
	v_add_u32_e32 v107, v250, v246
	ds_read_b32 v252, v107
	v_add_u32_e32 v106, v205, v245
	s_waitcnt lgkmcnt(1)
	v_fmac_f32_e32 v251, 0x3e38aa3b, v108
	v_add_u32_e32 v107, v205, v246
	v_add_u32_e32 v108, v250, v247
	ds_read_b32 v106, v106
	ds_read_b32 v107, v107
	ds_read_b32 v253, v108
	s_waitcnt lgkmcnt(3)
	v_fmac_f32_e32 v252, 0x3e38aa3b, v109
	v_add_u32_e32 v109, v250, v248
	ds_read_b32 v250, v109
	v_add_u32_e32 v108, v205, v247
	s_waitcnt lgkmcnt(1)
	v_fmac_f32_e32 v253, 0x3e38aa3b, v110
	v_add_u32_e32 v109, v205, v248
	v_add_u32_e32 v110, v212, v213
	ds_read_b32 v108, v108
	ds_read_b32 v109, v109
	s_waitcnt vmcnt(3)
	ds_write_b128 v110, v[148:151]
	s_waitcnt vmcnt(2)
	ds_write_b128 v110, v[152:155] offset:512
	s_waitcnt vmcnt(1)
	ds_write_b128 v110, v[156:159] offset:1024
	s_waitcnt vmcnt(0)
	ds_write_b128 v110, v[160:163] offset:1536
	v_max_f32_e32 v110, v164, v165
	v_max3_f32 v110, v110, v166, v167
	v_max3_f32 v110, v110, v168, v169
	v_max3_f32 v110, v110, v170, v171
	v_max3_f32 v110, v110, v172, v173
	v_max3_f32 v110, v110, v174, v175
	s_waitcnt lgkmcnt(6)
	v_fmac_f32_e32 v250, 0x3e38aa3b, v111
	v_max3_f32 v110, v110, v251, v252
	v_max3_f32 v110, v110, v253, v250
	v_mov_b32_e32 v111, v110
	s_nop 1
	v_permlane32_swap_b32 v110, v111
	s_nop 1
	s_nop 0
	v_max_f32_e32 v110, v110, v111
	v_add_f32_e32 v111, 0x41000000, v14
	v_cmp_gt_f32_e32 vcc, v110, v111
	s_cbranch_vccz .LBB0_496
	v_max_f32_e32 v110, v110, v110
	v_max_f32_e32 v111, v14, v14
	v_max_f32_e32 v110, v111, v110
	v_sub_f32_e32 v14, v14, v110
	v_exp_f32_e32 v14, v14
	s_nop 0
	v_mul_f32_e32 v220, v220, v14
	v_pk_mul_f32 v[78:79], v[78:79], v[14:15] op_sel_hi:[1,0]
	v_pk_mul_f32 v[76:77], v[76:77], v[14:15] op_sel_hi:[1,0]
	v_pk_mul_f32 v[74:75], v[74:75], v[14:15] op_sel_hi:[1,0]
	v_pk_mul_f32 v[72:73], v[72:73], v[14:15] op_sel_hi:[1,0]
	v_pk_mul_f32 v[70:71], v[70:71], v[14:15] op_sel_hi:[1,0]
	v_pk_mul_f32 v[68:69], v[68:69], v[14:15] op_sel_hi:[1,0]
	v_pk_mul_f32 v[66:67], v[66:67], v[14:15] op_sel_hi:[1,0]
	v_pk_mul_f32 v[64:65], v[64:65], v[14:15] op_sel_hi:[1,0]
	v_pk_mul_f32 v[62:63], v[62:63], v[14:15] op_sel_hi:[1,0]
	v_pk_mul_f32 v[60:61], v[60:61], v[14:15] op_sel_hi:[1,0]
	v_pk_mul_f32 v[58:59], v[58:59], v[14:15] op_sel_hi:[1,0]
	v_pk_mul_f32 v[56:57], v[56:57], v[14:15] op_sel_hi:[1,0]
	v_pk_mul_f32 v[54:55], v[54:55], v[14:15] op_sel_hi:[1,0]
	v_pk_mul_f32 v[52:53], v[52:53], v[14:15] op_sel_hi:[1,0]
	v_pk_mul_f32 v[50:51], v[50:51], v[14:15] op_sel_hi:[1,0]
	v_pk_mul_f32 v[48:49], v[48:49], v[14:15] op_sel_hi:[1,0]
	v_mov_b32_e32 v14, v110
; #define LAS __attribute__((address_space(3)))
; __device__ __forceinline__ unsigned cvtpk(float lo, float hi) { f32x2 v = {lo, hi}; bf16x2_t b = __builtin_convertvector(v, bf16x2_t); return __builtin_bit_cast(unsigned, b); }
; __device__ __forceinline__ float xhalf_max(float v) { float a = v, b = v; xhalf_swap(a, b); return fmaxf(a, b); }
; #define VFRAG(off) ({ const s16x4 lo_ = vtr(vb + (off)); const s16x4 hi_ = vtr(vb + (off) + 512); (bf16x8){lo_[0], lo_[1], lo_[2], lo_[3], hi_[0], hi_[1], hi_[2], hi_[3]}; })
; __device__ __forceinline__ void softmax_pv(WaveAttn& st, f32x16 s, LAS const unsigned char* vb, int lane) {
;     float mx = s[0];
; #pragma unroll
;     for (int r = 1; r < 16; ++r) mx = fmaxf(mx, s[r]);
;     mx = xhalf_max(mx);
;     if (__builtin_amdgcn_ballot_w64(mx > st.m + 8.0f) != 0ull) {
;         const float mn = fmaxf(st.m, mx);
;         const float alpha = __builtin_amdgcn_exp2f(st.m - mn);
;         st.m = mn; st.l *= alpha;
; #pragma unroll
;         for (int r = 0; r < 16; ++r) { st.o0[r] *= alpha; st.o1[r] *= alpha; }
;     }
;     const float mn = st.m;
;     float ps = 0.f;
; #pragma unroll
;     for (int r = 0; r < 16; ++r) { s[r] = __builtin_amdgcn_exp2f(s[r] - mn); ps += s[r]; }
;     st.l += ps;
;     u32x4 p0, p1;
;     p0.x = cvtpk(s[0], s[1]); p0.y = cvtpk(s[2], s[3]); p0.z = cvtpk(s[4], s[5]); p0.w = cvtpk(s[6], s[7]);
;     p1.x = cvtpk(s[8], s[9]); p1.y = cvtpk(s[10], s[11]); p1.z = cvtpk(s[12], s[13]); p1.w = cvtpk(s[14], s[15]);
;     const bf16x8 pb0 = __builtin_bit_cast(bf16x8, p0), pb1 = __builtin_bit_cast(bf16x8, p1);
;     ...
;     { const bf16x8 v00 = VFRAG(0), v01 = VFRAG(1024), v10 = VFRAG(2048), v11 = VFRAG(2048 + 1024);
;       st.o0 = __builtin_amdgcn_mfma_f32_32x32x16_bf16(v00, pb0, st.o0, 0, 0, 0);
;       st.o0 = __builtin_amdgcn_mfma_f32_32x32x16_bf16(v01, pb1, st.o0, 0, 0, 0);
;       st.o1 = __builtin_amdgcn_mfma_f32_32x32x16_bf16(v10, pb0, st.o1, 0, 0, 0);
;       st.o1 = __builtin_amdgcn_mfma_f32_32x32x16_bf16(v11, pb1, st.o1, 0, 0, 0); }
.LBB0_496:
	v_fmac_f32_e32 v0, 0x3e38aa3b, v80
	v_sub_f32_e32 v80, v164, v14
	v_fmac_f32_e32 v15, 0x3e38aa3b, v81
	v_exp_f32_e32 v81, v80
	v_sub_f32_e32 v80, v165, v14
	v_fmac_f32_e32 v96, 0x3e38aa3b, v82
	v_exp_f32_e32 v82, v80
	v_sub_f32_e32 v80, v166, v14
	v_fmac_f32_e32 v97, 0x3e38aa3b, v83
	v_exp_f32_e32 v83, v80
	v_sub_f32_e32 v80, v167, v14
	v_fmac_f32_e32 v98, 0x3e38aa3b, v84
	v_exp_f32_e32 v84, v80
	v_sub_f32_e32 v80, v168, v14
	v_fmac_f32_e32 v99, 0x3e38aa3b, v85
	v_exp_f32_e32 v85, v80
	v_sub_f32_e32 v80, v169, v14
	v_fmac_f32_e32 v100, 0x3e38aa3b, v86
	v_exp_f32_e32 v86, v80
	v_sub_f32_e32 v80, v170, v14
	v_fmac_f32_e32 v101, 0x3e38aa3b, v87
	v_exp_f32_e32 v87, v80
	v_sub_f32_e32 v80, v171, v14
	v_fmac_f32_e32 v102, 0x3e38aa3b, v88
	v_exp_f32_e32 v88, v80
	v_sub_f32_e32 v80, v172, v14
	v_fmac_f32_e32 v103, 0x3e38aa3b, v89
	v_exp_f32_e32 v89, v80
	v_sub_f32_e32 v80, v173, v14
	v_fmac_f32_e32 v104, 0x3e38aa3b, v90
	v_exp_f32_e32 v90, v80
	v_sub_f32_e32 v80, v174, v14
	v_fmac_f32_e32 v105, 0x3e38aa3b, v91
	v_exp_f32_e32 v91, v80
	v_sub_f32_e32 v80, v175, v14
	v_fmac_f32_e32 v107, 0x3e38aa3b, v93
	v_exp_f32_e32 v93, v80
	v_sub_f32_e32 v80, v251, v14
	s_waitcnt lgkmcnt(5)
	v_fmac_f32_e32 v108, 0x3e38aa3b, v94
	v_exp_f32_e32 v94, v80
	v_sub_f32_e32 v80, v252, v14
	s_waitcnt lgkmcnt(4)
	v_fmac_f32_e32 v109, 0x3e38aa3b, v95
	v_exp_f32_e32 v95, v80
	v_sub_f32_e32 v80, v253, v14
	v_exp_f32_e32 v110, v80
	v_sub_f32_e32 v80, v250, v14
	v_fmac_f32_e32 v106, 0x3e38aa3b, v92
	v_exp_f32_e32 v92, v80
	v_add_u32_e32 v80, v214, v211
	ds_read_b64_tr_b16 v[156:157], v80
	ds_read_b64_tr_b16 v[158:159], v80 offset:512
	ds_read_b64_tr_b16 v[160:161], v80 offset:1024
	ds_read_b64_tr_b16 v[162:163], v80 offset:1536
	ds_read_b64_tr_b16 v[164:165], v80 offset:2048
	ds_read_b64_tr_b16 v[166:167], v80 offset:2560
	ds_read_b64_tr_b16 v[168:169], v80 offset:3072
	ds_read_b64_tr_b16 v[170:171], v80 offset:3584
	v_cvt_pk_bf16_f32 v148, v81, v82
	v_cvt_pk_bf16_f32 v149, v83, v84
	v_cvt_pk_bf16_f32 v150, v85, v86
	v_cvt_pk_bf16_f32 v151, v87, v88
	v_max_f32_e32 v111, v0, v15
	v_max3_f32 v111, v111, v96, v97
	s_waitcnt lgkmcnt(6)
	v_mfma_f32_32x32x16_bf16 v[64:79], v[156:159], v[148:151], v[64:79]
	v_max3_f32 v111, v111, v98, v99
	v_max3_f32 v111, v111, v100, v101
	v_cvt_pk_bf16_f32 v152, v89, v90
	v_cvt_pk_bf16_f32 v153, v91, v93
	v_cvt_pk_bf16_f32 v154, v94, v95
	v_cvt_pk_bf16_f32 v155, v110, v92
	v_max3_f32 v111, v111, v102, v103
	s_waitcnt lgkmcnt(2)
	v_mfma_f32_32x32x16_bf16 v[48:63], v[164:167], v[148:151], v[48:63]
	v_max3_f32 v111, v111, v104, v105
	v_max3_f32 v111, v111, v106, v107
	v_max3_f32 v111, v111, v108, v109
	v_mov_b32_e32 v148, v111
	s_nop 1
	v_permlane32_swap_b32 v111, v148
	s_nop 1
	s_nop 0
	v_mfma_f32_32x32x16_bf16 v[64:79], v[160:163], v[152:155], v[64:79]
	v_max_f32_e32 v111, v111, v148
	v_add_f32_e32 v148, 0x41000000, v249
	v_cmp_gt_f32_e32 vcc, v111, v148
	s_waitcnt lgkmcnt(0)
	v_mfma_f32_32x32x16_bf16 v[48:63], v[168:171], v[152:155], v[48:63]
	s_cbranch_vccz .LBB0_491
	v_max_f32_e32 v111, v249, v111
	v_sub_f32_e32 v148, v249, v111
	v_exp_f32_e32 v148, v148
	v_mov_b32_e32 v249, v111
	v_mul_f32_e32 v193, v193, v148
	v_pk_mul_f32 v[46:47], v[46:47], v[148:149] op_sel_hi:[1,0]
	v_pk_mul_f32 v[44:45], v[44:45], v[148:149] op_sel_hi:[1,0]
	v_pk_mul_f32 v[42:43], v[42:43], v[148:149] op_sel_hi:[1,0]
	v_pk_mul_f32 v[40:41], v[40:41], v[148:149] op_sel_hi:[1,0]
	v_pk_mul_f32 v[38:39], v[38:39], v[148:149] op_sel_hi:[1,0]
	v_pk_mul_f32 v[36:37], v[36:37], v[148:149] op_sel_hi:[1,0]
	v_pk_mul_f32 v[34:35], v[34:35], v[148:149] op_sel_hi:[1,0]
	v_pk_mul_f32 v[32:33], v[32:33], v[148:149] op_sel_hi:[1,0]
	v_pk_mul_f32 v[30:31], v[30:31], v[148:149] op_sel_hi:[1,0]
	v_pk_mul_f32 v[28:29], v[28:29], v[148:149] op_sel_hi:[1,0]
	v_pk_mul_f32 v[26:27], v[26:27], v[148:149] op_sel_hi:[1,0]
	v_pk_mul_f32 v[24:25], v[24:25], v[148:149] op_sel_hi:[1,0]
	v_pk_mul_f32 v[22:23], v[22:23], v[148:149] op_sel_hi:[1,0]
	v_pk_mul_f32 v[20:21], v[20:21], v[148:149] op_sel_hi:[1,0]
	v_pk_mul_f32 v[18:19], v[18:19], v[148:149] op_sel_hi:[1,0]
	v_pk_mul_f32 v[16:17], v[16:17], v[148:149] op_sel_hi:[1,0]
	s_branch .LBB0_491

; #define LAS __attribute__((address_space(3)))
; __device__ __forceinline__ unsigned cvtpk(float lo, float hi) { f32x2 v = {lo, hi}; bf16x2_t b = __builtin_convertvector(v, bf16x2_t); return __builtin_bit_cast(unsigned, b); }
; __device__ __forceinline__ float xhalf_max(float v) { float a = v, b = v; xhalf_swap(a, b); return fmaxf(a, b); }
; #define VFRAG(off) ({ const s16x4 lo_ = vtr(vb + (off)); const s16x4 hi_ = vtr(vb + (off) + 512); (bf16x8){lo_[0], lo_[1], lo_[2], lo_[3], hi_[0], hi_[1], hi_[2], hi_[3]}; })
; __device__ __forceinline__ void softmax_pv(WaveAttn& st, f32x16 s, LAS const unsigned char* vb, int lane) {
;     float mx = s[0];
; #pragma unroll
;     for (int r = 1; r < 16; ++r) mx = fmaxf(mx, s[r]);
;     mx = xhalf_max(mx);
;     if (__builtin_amdgcn_ballot_w64(mx > st.m + 8.0f) != 0ull) {
;         const float mn = fmaxf(st.m, mx);
;         const float alpha = __builtin_amdgcn_exp2f(st.m - mn);
;         st.m = mn; st.l *= alpha;
; #pragma unroll
;         for (int r = 0; r < 16; ++r) { st.o0[r] *= alpha; st.o1[r] *= alpha; }
;     }
;     const float mn = st.m;
;     float ps = 0.f;
; #pragma unroll
;     for (int r = 0; r < 16; ++r) { s[r] = __builtin_amdgcn_exp2f(s[r] - mn); ps += s[r]; }
;     st.l += ps;
;     u32x4 p0, p1;
;     p0.x = cvtpk(s[0], s[1]); p0.y = cvtpk(s[2], s[3]); p0.z = cvtpk(s[4], s[5]); p0.w = cvtpk(s[6], s[7]);
;     p1.x = cvtpk(s[8], s[9]); p1.y = cvtpk(s[10], s[11]); p1.z = cvtpk(s[12], s[13]); p1.w = cvtpk(s[14], s[15]);
;     const bf16x8 pb0 = __builtin_bit_cast(bf16x8, p0), pb1 = __builtin_bit_cast(bf16x8, p1);
;     ...
;     { const bf16x8 v00 = VFRAG(0), v01 = VFRAG(1024), v10 = VFRAG(2048), v11 = VFRAG(2048 + 1024);
;       st.o0 = __builtin_amdgcn_mfma_f32_32x32x16_bf16(v00, pb0, st.o0, 0, 0, 0);
;       st.o0 = __builtin_amdgcn_mfma_f32_32x32x16_bf16(v01, pb1, st.o0, 0, 0, 0);
;       st.o1 = __builtin_amdgcn_mfma_f32_32x32x16_bf16(v10, pb0, st.o1, 0, 0, 0);
;       st.o1 = __builtin_amdgcn_mfma_f32_32x32x16_bf16(v11, pb1, st.o1, 0, 0, 0); }
.LBB0_510:
	s_or_b64 exec, exec, s[80:81]
	v_add_u32_e32 v162, v212, v213
	s_waitcnt vmcnt(3)
	ds_write_b128 v162, v[146:149]
	s_waitcnt vmcnt(2)
	ds_write_b128 v162, v[150:153] offset:512
	s_waitcnt vmcnt(1)
	ds_write_b128 v162, v[154:157] offset:1024
	s_waitcnt vmcnt(0)
	ds_write_b128 v162, v[158:161] offset:1536
	v_max_f32_e32 v146, v82, v83
	v_max3_f32 v146, v146, v84, v85
	v_max3_f32 v146, v146, v86, v87
	v_max3_f32 v146, v146, v88, v89
	v_max3_f32 v146, v146, v90, v91
	v_max3_f32 v146, v146, v92, v93
	v_max3_f32 v146, v146, v94, v95
	v_max3_f32 v146, v146, v96, v97
	v_mov_b32_e32 v147, v146
	s_nop 1
	v_permlane32_swap_b32 v146, v147
	s_nop 1
	s_nop 0
	v_max_f32_e32 v146, v146, v147
	v_add_f32_e32 v147, 0x41000000, v203
	v_cmp_gt_f32_e32 vcc, v146, v147
	s_cbranch_vccz .LBB0_512
	v_max_f32_e32 v147, v203, v146
	v_sub_f32_e32 v146, v203, v147
	v_exp_f32_e32 v146, v146
	v_mov_b32_e32 v203, v147
	v_mul_f32_e32 v197, v197, v146
	v_pk_mul_f32 v[48:49], v[48:49], v[146:147] op_sel_hi:[1,0]
	v_pk_mul_f32 v[46:47], v[46:47], v[146:147] op_sel_hi:[1,0]
	v_pk_mul_f32 v[44:45], v[44:45], v[146:147] op_sel_hi:[1,0]
	v_pk_mul_f32 v[42:43], v[42:43], v[146:147] op_sel_hi:[1,0]
	v_pk_mul_f32 v[40:41], v[40:41], v[146:147] op_sel_hi:[1,0]
	v_pk_mul_f32 v[38:39], v[38:39], v[146:147] op_sel_hi:[1,0]
	v_pk_mul_f32 v[36:37], v[36:37], v[146:147] op_sel_hi:[1,0]
	v_pk_mul_f32 v[34:35], v[34:35], v[146:147] op_sel_hi:[1,0]
	v_pk_mul_f32 v[64:65], v[64:65], v[146:147] op_sel_hi:[1,0]
	v_pk_mul_f32 v[62:63], v[62:63], v[146:147] op_sel_hi:[1,0]
	v_pk_mul_f32 v[60:61], v[60:61], v[146:147] op_sel_hi:[1,0]
	v_pk_mul_f32 v[58:59], v[58:59], v[146:147] op_sel_hi:[1,0]
	v_pk_mul_f32 v[56:57], v[56:57], v[146:147] op_sel_hi:[1,0]
	v_pk_mul_f32 v[54:55], v[54:55], v[146:147] op_sel_hi:[1,0]
	v_pk_mul_f32 v[52:53], v[52:53], v[146:147] op_sel_hi:[1,0]
	v_pk_mul_f32 v[50:51], v[50:51], v[146:147] op_sel_hi:[1,0]
.LBB0_512:
	v_sub_f32_e32 v82, v82, v203
	v_exp_f32_e32 v146, v82
	v_sub_f32_e32 v82, v83, v203
	v_exp_f32_e32 v83, v82
	v_sub_f32_e32 v82, v84, v203
	v_exp_f32_e32 v84, v82
	v_sub_f32_e32 v82, v85, v203
	v_exp_f32_e32 v85, v82
	v_sub_f32_e32 v82, v86, v203
	v_exp_f32_e32 v86, v82
	v_sub_f32_e32 v82, v87, v203
	v_exp_f32_e32 v87, v82
	v_sub_f32_e32 v82, v88, v203
	v_exp_f32_e32 v88, v82
	v_sub_f32_e32 v82, v89, v203
	v_exp_f32_e32 v89, v82
	v_sub_f32_e32 v82, v90, v203
	v_exp_f32_e32 v90, v82
	v_sub_f32_e32 v82, v91, v203
	v_exp_f32_e32 v91, v82
	v_sub_f32_e32 v82, v92, v203
	v_exp_f32_e32 v92, v82
	v_sub_f32_e32 v82, v93, v203
	v_exp_f32_e32 v93, v82
	v_sub_f32_e32 v82, v94, v203
	v_exp_f32_e32 v94, v82
	v_add_u32_e32 v82, v214, v211
	ds_read_b64_tr_b16 v[148:149], v82
	ds_read_b64_tr_b16 v[150:151], v82 offset:512
	v_cvt_pk_bf16_f32 v152, v146, v83
	v_cvt_pk_bf16_f32 v153, v84, v85
	v_cvt_pk_bf16_f32 v154, v86, v87
	v_cvt_pk_bf16_f32 v155, v88, v89
	v_sub_f32_e32 v95, v95, v203
	v_sub_f32_e32 v96, v96, v203
	s_waitcnt lgkmcnt(0)
	v_mfma_f32_32x32x16_bf16 v[34:49], v[148:151], v[152:155], v[34:49]
	v_sub_f32_e32 v97, v97, v203
	v_exp_f32_e32 v95, v95
	ds_read_b64_tr_b16 v[156:157], v82 offset:1024
	ds_read_b64_tr_b16 v[158:159], v82 offset:1536
	v_exp_f32_e32 v96, v96
	v_exp_f32_e32 v97, v97
	v_cvt_pk_bf16_f32 v148, v90, v91
	v_cvt_pk_bf16_f32 v149, v92, v93
	v_cvt_pk_bf16_f32 v150, v94, v95
	v_cvt_pk_bf16_f32 v151, v96, v97
	v_max_f32_e32 v147, v67, v67
	s_waitcnt lgkmcnt(0)
	v_mfma_f32_32x32x16_bf16 v[34:49], v[156:159], v[148:151], v[34:49]
	ds_read_b64_tr_b16 v[156:157], v82 offset:2048
	ds_read_b64_tr_b16 v[158:159], v82 offset:2560
	ds_read_b64_tr_b16 v[160:161], v82 offset:3072
	ds_read_b64_tr_b16 v[162:163], v82 offset:3584
	s_waitcnt lgkmcnt(2)
	v_mfma_f32_32x32x16_bf16 v[50:65], v[156:159], v[152:155], v[50:65]
	s_waitcnt lgkmcnt(0)
	v_mfma_f32_32x32x16_bf16 v[50:65], v[160:163], v[148:151], v[50:65]
	v_max_f32_e32 v148, v66, v66
	v_max_f32_e32 v147, v148, v147
	v_max3_f32 v147, v147, v68, v69
	v_max3_f32 v147, v147, v70, v71
	v_max3_f32 v147, v147, v72, v73
	v_max3_f32 v147, v147, v74, v75
	v_max3_f32 v147, v147, v76, v77
	v_max3_f32 v147, v147, v78, v79
	v_max3_f32 v147, v147, v80, v81
	v_mov_b32_e32 v148, v147
	s_nop 1
	v_permlane32_swap_b32 v148, v147
	s_nop 1
	s_nop 0
	v_max_f32_e32 v147, v148, v147
	v_add_f32_e32 v148, 0x41000000, v193
	v_cmp_gt_f32_e32 vcc, v147, v148
	s_cbranch_vccz .LBB0_505
	v_max_f32_e32 v147, v193, v147
	v_sub_f32_e32 v148, v193, v147
	v_exp_f32_e32 v148, v148
	v_mov_b32_e32 v193, v147
	v_mul_f32_e32 v175, v175, v148
	v_pk_mul_f32 v[16:17], v[16:17], v[148:149] op_sel_hi:[1,0]
	v_pk_mul_f32 v[14:15], v[14:15], v[148:149] op_sel_hi:[1,0]
	v_pk_mul_f32 v[12:13], v[12:13], v[148:149] op_sel_hi:[1,0]
	v_pk_mul_f32 v[10:11], v[10:11], v[148:149] op_sel_hi:[1,0]
	v_pk_mul_f32 v[8:9], v[8:9], v[148:149] op_sel_hi:[1,0]
	v_pk_mul_f32 v[6:7], v[6:7], v[148:149] op_sel_hi:[1,0]
	v_pk_mul_f32 v[4:5], v[4:5], v[148:149] op_sel_hi:[1,0]
	v_pk_mul_f32 v[2:3], v[2:3], v[148:149] op_sel_hi:[1,0]
	v_pk_mul_f32 v[32:33], v[32:33], v[148:149] op_sel_hi:[1,0]
	v_pk_mul_f32 v[30:31], v[30:31], v[148:149] op_sel_hi:[1,0]
	v_pk_mul_f32 v[28:29], v[28:29], v[148:149] op_sel_hi:[1,0]
	v_pk_mul_f32 v[26:27], v[26:27], v[148:149] op_sel_hi:[1,0]
	v_pk_mul_f32 v[24:25], v[24:25], v[148:149] op_sel_hi:[1,0]
	v_pk_mul_f32 v[22:23], v[22:23], v[148:149] op_sel_hi:[1,0]
	v_pk_mul_f32 v[20:21], v[20:21], v[148:149] op_sel_hi:[1,0]
	v_pk_mul_f32 v[18:19], v[18:19], v[148:149] op_sel_hi:[1,0]
	s_branch .LBB0_505

; __device__ __forceinline__ unsigned cvtpk(float lo, float hi) { f32x2 v = {lo, hi}; bf16x2_t b = __builtin_convertvector(v, bf16x2_t); return __builtin_bit_cast(unsigned, b); }
; #define VFRAG(off) ({ const s16x4 lo_ = vtr(vb + (off)); const s16x4 hi_ = vtr(vb + (off) + 512); (bf16x8){lo_[0], lo_[1], lo_[2], lo_[3], hi_[0], hi_[1], hi_[2], hi_[3]}; })
; __device__ __forceinline__ void softmax_pv(WaveAttn& st, f32x16 s, LAS const unsigned char* vb, int lane) {
;     ...
;     const float mn = st.m;
;     float ps = 0.f;
; #pragma unroll
;     for (int r = 0; r < 16; ++r) { s[r] = __builtin_amdgcn_exp2f(s[r] - mn); ps += s[r]; }
;     st.l += ps;
;     u32x4 p0, p1;
;     p0.x = cvtpk(s[0], s[1]); p0.y = cvtpk(s[2], s[3]); p0.z = cvtpk(s[4], s[5]); p0.w = cvtpk(s[6], s[7]);
;     p1.x = cvtpk(s[8], s[9]); p1.y = cvtpk(s[10], s[11]); p1.z = cvtpk(s[12], s[13]); p1.w = cvtpk(s[14], s[15]);
;     const bf16x8 pb0 = __builtin_bit_cast(bf16x8, p0), pb1 = __builtin_bit_cast(bf16x8, p1);
;     ...
;     { const bf16x8 v00 = VFRAG(0), v01 = VFRAG(1024), v10 = VFRAG(2048), v11 = VFRAG(2048 + 1024);
;       st.o0 = __builtin_amdgcn_mfma_f32_32x32x16_bf16(v00, pb0, st.o0, 0, 0, 0);
;       st.o0 = __builtin_amdgcn_mfma_f32_32x32x16_bf16(v01, pb1, st.o0, 0, 0, 0);
;       st.o1 = __builtin_amdgcn_mfma_f32_32x32x16_bf16(v10, pb0, st.o1, 0, 0, 0);
;       st.o1 = __builtin_amdgcn_mfma_f32_32x32x16_bf16(v11, pb1, st.o1, 0, 0, 0); }
.LBB0_520:
	v_add_f32_e32 v94, v95, v94
	v_add_f32_e32 v94, v96, v94
	v_add_f32_e32 v94, v97, v94
	v_add_f32_e32 v94, v98, v94
	v_add_f32_e32 v94, v99, v94
	v_add_f32_e32 v94, v100, v94
	v_add_f32_e32 v94, v101, v94
	v_add_f32_e32 v94, v102, v94
	v_add_f32_e32 v94, v103, v94
	v_add_f32_e32 v94, v104, v94
	v_add_f32_e32 v94, v105, v94
	v_add_f32_e32 v94, v106, v94
	v_add_f32_e32 v94, v107, v94
	v_sub_f32_e32 v80, v80, v220
	v_add_f32_e32 v94, v109, v94
	v_exp_f32_e32 v95, v80
	v_sub_f32_e32 v81, v81, v220
	v_add_f32_e32 v80, v108, v94
	v_exp_f32_e32 v94, v81
	v_sub_f32_e32 v81, v82, v220
	v_exp_f32_e32 v96, v81
	v_sub_f32_e32 v81, v83, v220
	v_exp_f32_e32 v97, v81
	v_sub_f32_e32 v81, v84, v220
	v_add_f32_e32 v201, v201, v80
	v_add_f32_e32 v80, 0, v95
	v_exp_f32_e32 v98, v81
	v_add_f32_e32 v80, v94, v80
	v_add_f32_e32 v80, v96, v80
	v_add_f32_e32 v80, v97, v80
	v_add_f32_e32 v99, v98, v80
	v_sub_f32_e32 v80, v85, v220
	v_exp_f32_e32 v100, v80
	v_sub_f32_e32 v80, v86, v220
	v_exp_f32_e32 v101, v80
	v_sub_f32_e32 v80, v87, v220
	v_exp_f32_e32 v102, v80
	v_sub_f32_e32 v80, v88, v220
	v_exp_f32_e32 v103, v80
	v_sub_f32_e32 v80, v89, v220
	v_exp_f32_e32 v104, v80
	v_sub_f32_e32 v80, v90, v220
	v_exp_f32_e32 v105, v80
	v_sub_f32_e32 v80, v91, v220
	v_exp_f32_e32 v106, v80
	v_sub_f32_e32 v80, v92, v220
	v_exp_f32_e32 v107, v80
	v_sub_f32_e32 v80, v93, v220
	v_exp_f32_e32 v108, v80
	ds_read_b64_tr_b16 v[80:81], v0
	ds_read_b64_tr_b16 v[82:83], v0 offset:512
	v_cvt_pk_bf16_f32 v84, v95, v94
	v_cvt_pk_bf16_f32 v85, v96, v97
	v_cvt_pk_bf16_f32 v86, v98, v100
	v_cvt_pk_bf16_f32 v87, v101, v102
	v_sub_f32_e32 v14, v14, v220
	v_sub_f32_e32 v15, v15, v220
	s_waitcnt lgkmcnt(0)
	v_mfma_f32_32x32x16_bf16 v[32:47], v[80:83], v[84:87], v[32:47]
	v_exp_f32_e32 v14, v14
	ds_read_b64_tr_b16 v[88:89], v0 offset:1024
	ds_read_b64_tr_b16 v[90:91], v0 offset:1536
	v_exp_f32_e32 v15, v15
	ds_read_b64_tr_b16 v[92:93], v0 offset:2048
	ds_read_b64_tr_b16 v[94:95], v0 offset:2560
	v_cvt_pk_bf16_f32 v80, v103, v104
	v_cvt_pk_bf16_f32 v81, v105, v106
	v_cvt_pk_bf16_f32 v82, v107, v108
	v_cvt_pk_bf16_f32 v83, v14, v15
	s_waitcnt lgkmcnt(0)
	v_mfma_f32_32x32x16_bf16 v[16:31], v[92:95], v[84:87], v[16:31]
	s_and_b64 s[0:1], exec, s[4:5]
	v_mov_b64_e32 v[166:167], v[8:9]
	v_mov_b64_e32 v[174:175], v[12:13]
	v_mov_b64_e32 v[170:171], v[146:147]
	s_or_b64 s[78:79], s[0:1], s[78:79]
	v_add_u32_e32 v236, 0x80, v236
	v_add_u32_e32 v235, 32, v235
	v_mfma_f32_32x32x16_bf16 v[32:47], v[88:91], v[80:83], v[32:47]
	v_add_f32_e32 v88, v100, v99
	v_add_f32_e32 v88, v101, v88
	v_add_f32_e32 v88, v102, v88
	v_add_f32_e32 v88, v103, v88
	v_add_f32_e32 v96, v104, v88
	ds_read_b64_tr_b16 v[88:89], v0 offset:3072
	ds_read_b64_tr_b16 v[90:91], v0 offset:3584
	v_add_f32_e32 v0, v105, v96
	s_waitcnt lgkmcnt(0)
	v_mfma_f32_32x32x16_bf16 v[16:31], v[88:91], v[80:83], v[16:31]
	v_add_f32_e32 v0, v106, v0
	v_add_f32_e32 v0, v107, v0
	v_add_f32_e32 v0, v108, v0
	v_add_f32_e32 v0, v14, v0
	v_add_f32_e32 v0, v15, v0
	v_mov_b64_e32 v[82:83], v[4:5]
	v_add_f32_e32 v197, v197, v0
	v_mov_b64_e32 v[80:81], v[2:3]
	v_mov_b64_e32 v[164:165], v[6:7]
	v_mov_b64_e32 v[172:173], v[10:11]
	v_mov_b64_e32 v[168:169], v[144:145]
	s_andn2_b64 exec, exec, s[78:79]
	s_cbranch_execz .LBB0_529

; #define LAS __attribute__((address_space(3)))
; __device__ __forceinline__ unsigned cvtpk(float lo, float hi) { f32x2 v = {lo, hi}; bf16x2_t b = __builtin_convertvector(v, bf16x2_t); return __builtin_bit_cast(unsigned, b); }
; __device__ __forceinline__ float xhalf_max(float v) { float a = v, b = v; xhalf_swap(a, b); return fmaxf(a, b); }
; #define VFRAG(off) ({ const s16x4 lo_ = vtr(vb + (off)); const s16x4 hi_ = vtr(vb + (off) + 512); (bf16x8){lo_[0], lo_[1], lo_[2], lo_[3], hi_[0], hi_[1], hi_[2], hi_[3]}; })
; __device__ __forceinline__ void softmax_pv(WaveAttn& st, f32x16 s, LAS const unsigned char* vb, int lane) {
;     float mx = s[0];
; #pragma unroll
;     for (int r = 1; r < 16; ++r) mx = fmaxf(mx, s[r]);
;     mx = xhalf_max(mx);
;     if (__builtin_amdgcn_ballot_w64(mx > st.m + 8.0f) != 0ull) {
;         const float mn = fmaxf(st.m, mx);
;         const float alpha = __builtin_amdgcn_exp2f(st.m - mn);
;         st.m = mn; st.l *= alpha;
; #pragma unroll
;         for (int r = 0; r < 16; ++r) { st.o0[r] *= alpha; st.o1[r] *= alpha; }
;     }
;     const float mn = st.m;
;     float ps = 0.f;
; #pragma unroll
;     for (int r = 0; r < 16; ++r) { s[r] = __builtin_amdgcn_exp2f(s[r] - mn); ps += s[r]; }
;     st.l += ps;
;     u32x4 p0, p1;
;     p0.x = cvtpk(s[0], s[1]); p0.y = cvtpk(s[2], s[3]); p0.z = cvtpk(s[4], s[5]); p0.w = cvtpk(s[6], s[7]);
;     p1.x = cvtpk(s[8], s[9]); p1.y = cvtpk(s[10], s[11]); p1.z = cvtpk(s[12], s[13]); p1.w = cvtpk(s[14], s[15]);
;     const bf16x8 pb0 = __builtin_bit_cast(bf16x8, p0), pb1 = __builtin_bit_cast(bf16x8, p1);
;     ...
;     { const bf16x8 v00 = VFRAG(0), v01 = VFRAG(1024), v10 = VFRAG(2048), v11 = VFRAG(2048 + 1024);
;       st.o0 = __builtin_amdgcn_mfma_f32_32x32x16_bf16(v00, pb0, st.o0, 0, 0, 0);
;       st.o0 = __builtin_amdgcn_mfma_f32_32x32x16_bf16(v01, pb1, st.o0, 0, 0, 0);
;       st.o1 = __builtin_amdgcn_mfma_f32_32x32x16_bf16(v10, pb0, st.o1, 0, 0, 0);
;       st.o1 = __builtin_amdgcn_mfma_f32_32x32x16_bf16(v11, pb1, st.o1, 0, 0, 0); }
.LBB0_525:
	s_or_b64 exec, exec, s[8:9]
	v_add_u32_e32 v0, v212, v213
	s_waitcnt vmcnt(3)
	ds_write_b128 v0, v[148:151]
	s_waitcnt vmcnt(2)
	ds_write_b128 v0, v[152:155] offset:512
	s_waitcnt vmcnt(1)
	ds_write_b128 v0, v[156:159] offset:1024
	s_waitcnt vmcnt(0)
	ds_write_b128 v0, v[160:163] offset:1536
	v_max_f32_e32 v0, v96, v97
	v_max3_f32 v0, v0, v98, v99
	v_max3_f32 v0, v0, v100, v101
	v_max3_f32 v0, v0, v102, v103
	v_max3_f32 v0, v0, v104, v105
	v_max3_f32 v0, v0, v106, v107
	v_max3_f32 v0, v0, v108, v109
	v_max3_f32 v0, v0, v110, v111
	v_mov_b32_e32 v94, v0
	s_nop 1
	v_permlane32_swap_b32 v0, v94
	s_nop 1
	s_nop 0
	v_max_f32_e32 v0, v0, v94
	v_add_f32_e32 v94, 0x41000000, v222
	v_cmp_gt_f32_e32 vcc, v0, v94
	s_cbranch_vccz .LBB0_527
	v_max_f32_e32 v94, v222, v0
	v_sub_f32_e32 v0, v222, v94
	v_exp_f32_e32 v0, v0
	v_mov_b32_e32 v222, v94
	v_mul_f32_e32 v201, v201, v0
	v_pk_mul_f32 v[78:79], v[78:79], v[0:1] op_sel_hi:[1,0]
	v_pk_mul_f32 v[76:77], v[76:77], v[0:1] op_sel_hi:[1,0]
	v_pk_mul_f32 v[74:75], v[74:75], v[0:1] op_sel_hi:[1,0]
	v_pk_mul_f32 v[72:73], v[72:73], v[0:1] op_sel_hi:[1,0]
	v_pk_mul_f32 v[70:71], v[70:71], v[0:1] op_sel_hi:[1,0]
	v_pk_mul_f32 v[68:69], v[68:69], v[0:1] op_sel_hi:[1,0]
	v_pk_mul_f32 v[66:67], v[66:67], v[0:1] op_sel_hi:[1,0]
	v_pk_mul_f32 v[64:65], v[64:65], v[0:1] op_sel_hi:[1,0]
	v_pk_mul_f32 v[62:63], v[62:63], v[0:1] op_sel_hi:[1,0]
	v_pk_mul_f32 v[60:61], v[60:61], v[0:1] op_sel_hi:[1,0]
	v_pk_mul_f32 v[58:59], v[58:59], v[0:1] op_sel_hi:[1,0]
	v_pk_mul_f32 v[56:57], v[56:57], v[0:1] op_sel_hi:[1,0]
	v_pk_mul_f32 v[54:55], v[54:55], v[0:1] op_sel_hi:[1,0]
	v_pk_mul_f32 v[52:53], v[52:53], v[0:1] op_sel_hi:[1,0]
	v_pk_mul_f32 v[50:51], v[50:51], v[0:1] op_sel_hi:[1,0]
	v_pk_mul_f32 v[48:49], v[48:49], v[0:1] op_sel_hi:[1,0]
.LBB0_527:
	v_sub_f32_e32 v0, v96, v222
	v_exp_f32_e32 v94, v0
	v_sub_f32_e32 v0, v97, v222
	v_exp_f32_e32 v95, v0
	v_sub_f32_e32 v0, v98, v222
	v_exp_f32_e32 v96, v0
	v_sub_f32_e32 v0, v99, v222
	v_exp_f32_e32 v97, v0
	v_sub_f32_e32 v0, v100, v222
	v_exp_f32_e32 v98, v0
	v_sub_f32_e32 v0, v101, v222
	v_exp_f32_e32 v99, v0
	v_sub_f32_e32 v0, v102, v222
	v_exp_f32_e32 v100, v0
	v_sub_f32_e32 v0, v103, v222
	v_exp_f32_e32 v101, v0
	v_sub_f32_e32 v0, v104, v222
	v_exp_f32_e32 v102, v0
	v_sub_f32_e32 v0, v105, v222
	v_exp_f32_e32 v103, v0
	v_sub_f32_e32 v0, v106, v222
	v_exp_f32_e32 v104, v0
	v_sub_f32_e32 v0, v107, v222
	v_exp_f32_e32 v105, v0
	v_sub_f32_e32 v0, v108, v222
	v_exp_f32_e32 v106, v0
	v_add_u32_e32 v0, v214, v211
	ds_read_b64_tr_b16 v[148:149], v0
	ds_read_b64_tr_b16 v[150:151], v0 offset:512
	v_cvt_pk_bf16_f32 v152, v94, v95
	v_cvt_pk_bf16_f32 v153, v96, v97
	v_cvt_pk_bf16_f32 v154, v98, v99
	v_cvt_pk_bf16_f32 v155, v100, v101
	v_sub_f32_e32 v108, v110, v222
	v_sub_f32_e32 v107, v109, v222
	s_waitcnt lgkmcnt(0)
	v_mfma_f32_32x32x16_bf16 v[64:79], v[148:151], v[152:155], v[64:79]
	v_exp_f32_e32 v109, v108
	v_sub_f32_e32 v108, v111, v222
	v_exp_f32_e32 v107, v107
	ds_read_b64_tr_b16 v[156:157], v0 offset:1024
	ds_read_b64_tr_b16 v[158:159], v0 offset:1536
	v_exp_f32_e32 v108, v108
	v_cvt_pk_bf16_f32 v148, v102, v103
	v_cvt_pk_bf16_f32 v149, v104, v105
	v_cvt_pk_bf16_f32 v150, v106, v107
	v_cvt_pk_bf16_f32 v151, v109, v108
	s_waitcnt lgkmcnt(0)
	v_mfma_f32_32x32x16_bf16 v[64:79], v[156:159], v[148:151], v[64:79]
	ds_read_b64_tr_b16 v[156:157], v0 offset:2048
	ds_read_b64_tr_b16 v[158:159], v0 offset:2560
	ds_read_b64_tr_b16 v[160:161], v0 offset:3072
	ds_read_b64_tr_b16 v[162:163], v0 offset:3584
	v_max_f32_e32 v110, v80, v81
	v_max3_f32 v110, v110, v82, v83
	v_max3_f32 v110, v110, v84, v85
	v_max3_f32 v110, v110, v86, v87
	v_max3_f32 v110, v110, v88, v89
	s_waitcnt lgkmcnt(2)
	v_mfma_f32_32x32x16_bf16 v[48:63], v[156:159], v[152:155], v[48:63]
	v_max3_f32 v110, v110, v90, v91
	v_max3_f32 v110, v110, v92, v93
	v_max3_f32 v110, v110, v14, v15
	v_mov_b32_e32 v111, v110
	s_nop 1
	v_permlane32_swap_b32 v111, v110
	s_nop 1
	s_nop 0
	s_waitcnt lgkmcnt(0)
	v_mfma_f32_32x32x16_bf16 v[48:63], v[160:163], v[148:151], v[48:63]
	v_max_f32_e32 v110, v111, v110
	v_add_f32_e32 v111, 0x41000000, v220
	v_cmp_gt_f32_e32 vcc, v110, v111
	s_cbranch_vccz .LBB0_520
	v_max_f32_e32 v111, v220, v110
	v_sub_f32_e32 v110, v220, v111
	v_exp_f32_e32 v110, v110
	v_mov_b32_e32 v220, v111
	v_mul_f32_e32 v197, v197, v110
	v_pk_mul_f32 v[46:47], v[46:47], v[110:111] op_sel_hi:[1,0]
	v_pk_mul_f32 v[44:45], v[44:45], v[110:111] op_sel_hi:[1,0]
	v_pk_mul_f32 v[42:43], v[42:43], v[110:111] op_sel_hi:[1,0]
	v_pk_mul_f32 v[40:41], v[40:41], v[110:111] op_sel_hi:[1,0]
	v_pk_mul_f32 v[38:39], v[38:39], v[110:111] op_sel_hi:[1,0]
	v_pk_mul_f32 v[36:37], v[36:37], v[110:111] op_sel_hi:[1,0]
	v_pk_mul_f32 v[34:35], v[34:35], v[110:111] op_sel_hi:[1,0]
	v_pk_mul_f32 v[32:33], v[32:33], v[110:111] op_sel_hi:[1,0]
	v_pk_mul_f32 v[30:31], v[30:31], v[110:111] op_sel_hi:[1,0]
	v_pk_mul_f32 v[28:29], v[28:29], v[110:111] op_sel_hi:[1,0]
	v_pk_mul_f32 v[26:27], v[26:27], v[110:111] op_sel_hi:[1,0]
	v_pk_mul_f32 v[24:25], v[24:25], v[110:111] op_sel_hi:[1,0]
	v_pk_mul_f32 v[22:23], v[22:23], v[110:111] op_sel_hi:[1,0]
	v_pk_mul_f32 v[20:21], v[20:21], v[110:111] op_sel_hi:[1,0]
	v_pk_mul_f32 v[18:19], v[18:19], v[110:111] op_sel_hi:[1,0]
	v_pk_mul_f32 v[16:17], v[16:17], v[110:111] op_sel_hi:[1,0]
	s_branch .LBB0_520

; #define PG8_STAGE(bufoff, gbase, voff) do { _Pragma("unroll") for (int _i = 0; _i < 2; ++_i) \
;         __builtin_amdgcn_global_load_lds((const unsigned*)((const char*)(gbase) + (voff)[_i]), (LAS unsigned*)(lds + (bufoff) + ldsw + _i * 8192), 16, 0, 0); } while (0)
; #define PG8_WAIT_V(n) asm volatile("s_waitcnt vmcnt(" #n ")" ::: "memory")
; #define PG8_BAR __builtin_amdgcn_s_barrier()
; template <class Epi, class Sched>
; __device__ __forceinline__ void gemm_phase(LAS unsigned char* lds, const Gemm g, const Sched& S, const Epi& E, int wv) {
;     ...
;     const char* cA = (const char*)g.A + (size_t)cur.pm * tstepA + (size_t)cur.ak * 2; const char* cB = (const char*)g.Bt + (size_t)cur.pn * tstepB;
;     PG8_STAGE(PG8_SB(0, 0), cB, voffB); PG8_STAGE(PG8_SB(0, 1), cB + hstepB, voffB); PG8_STAGE(PG8_SA(0, 0), cA, voffA); PG8_STAGE(PG8_SA(0, 1), cA + hstepA, voffA);
;     if (wr == 1) PG8_BAR;
;     PG8_WAIT_V(2); PG8_BAR;
;     PG8_STAGE(PG8_SB(1, 0), cB + kstep, voffB); PG8_STAGE(PG8_SA(1, 0), cA + kstep, voffA); PG8_STAGE(PG8_SB(1, 1), cB + hstepB + kstep, voffB);
;     PG8_WAIT_V(6); PG8_BAR;
.LBB0_543:
	s_andn2_b64 vcc, exec, s[2:3]
	s_cbranch_vccnz .LBB0_695
	v_ashrrev_i32_e32 v4, 31, v2
	v_lshrrev_b32_e32 v4, 26, v4
	v_lshlrev_b32_e32 v3, 4, v2
	v_add_u32_e32 v4, v2, v4
	v_bfe_i32 v2, v2, 27, 1
	v_lshrrev_b32_e32 v2, 22, v2
	v_add_u32_e32 v2, v3, v2
	v_and_b32_e32 v2, 0xfffffc00, v2
	v_sub_u32_e32 v2, v3, v2
	s_waitcnt lgkmcnt(0)
	v_ashrrev_i32_e32 v10, 6, v4
	v_lshrrev_b32_e32 v4, 4, v2
	v_bitop3_b32 v2, v4, v2, 32 bitop3:0x6c
	v_ashrrev_i32_e32 v5, 31, v2
	v_lshrrev_b32_e32 v5, 26, v5
	v_add_u32_e32 v5, v2, v5
	v_ashrrev_i32_e32 v11, 6, v5
	v_and_b32_e32 v5, 0xc0, v5
	v_lshlrev_b32_e32 v4, 3, v10
	v_sub_u32_e32 v2, v2, v5
	v_and_b32_e32 v4, -16, v4
	v_lshlrev_b32_e32 v6, 5, v10
	v_ashrrev_i16_sdwa v2, v195, sext(v2) dst_sel:DWORD dst_unused:UNUSED_PAD src0_sel:DWORD src1_sel:BYTE_0
	v_add_u32_e32 v4, v11, v4
	v_and_b32_e32 v6, 32, v6
	v_bfe_i32 v12, v2, 0, 16
	v_add_u32_e32 v2, v6, v12
	v_lshlrev_b32_e32 v5, 13, v4
	v_lshl_add_u32 v196, v2, 1, v5
	v_add_u32_e32 v2, 0x2000, v3
	v_ashrrev_i32_e32 v3, 31, v2
	v_lshrrev_b32_e32 v3, 22, v3
	v_add_u32_e32 v3, v2, v3
	v_ashrrev_i32_e32 v13, 10, v3
	v_mul_i32_i24_e32 v3, 0x400, v13
	v_sub_u32_e32 v2, v2, v3
	v_lshrrev_b32_e32 v3, 4, v2
	s_movk_i32 s1, 0xe400
	v_bitop3_b32 v2, v3, v2, 32 bitop3:0x6c
	v_mad_u64_u32 v[198:199], s[2:3], v4, s1, v[196:197]
	v_ashrrev_i32_e32 v4, 31, v2
	v_lshrrev_b32_e32 v4, 26, v4
	v_add_u32_e32 v4, v2, v4
	v_ashrrev_i32_e32 v14, 6, v4
	v_and_b32_e32 v4, 0xc0, v4
	v_lshlrev_b32_e32 v3, 3, v13
	v_sub_u32_e32 v2, v2, v4
	v_and_b32_e32 v3, -16, v3
	v_lshlrev_b32_e32 v5, 5, v13
	v_ashrrev_i16_sdwa v2, v195, sext(v2) dst_sel:DWORD dst_unused:UNUSED_PAD src0_sel:DWORD src1_sel:BYTE_0
	s_add_u32 s46, s18, 0xa200000
	v_add_u32_e32 v3, v14, v3
	v_and_b32_e32 v5, 32, v5
	v_bfe_i32 v15, v2, 0, 16
	s_addc_u32 s47, s19, 0
	v_add_u32_e32 v2, v5, v15
	v_lshlrev_b32_e32 v4, 13, v3
	s_add_u32 s48, s57, 0x1000000
	v_lshl_add_u32 v200, v2, 1, v4
	s_addc_u32 s49, s58, 0
	v_mad_u64_u32 v[202:203], s[2:3], v3, s1, v[200:201]
	s_ashr_i32 s1, s10, 6
	s_ashr_i32 s7, s6, 31
	s_ashr_i32 s5, s4, 31
	s_ashr_i32 s0, s10, 8
	s_lshl_b32 s50, s1, 10
	s_lshl_b64 s[2:3], s[6:7], 21
	s_lshl_b64 s[8:9], s[4:5], 18
	s_add_u32 s80, s48, s8
	s_addc_u32 s81, s49, s9
	s_cmp_gt_u32 s4, 1
	s_cselect_b32 s32, 0x200, 0
	s_add_u32 s80, s80, s32
	s_addc_u32 s81, s81, 0
	s_add_i32 s60, s50, 0
	s_add_i32 m0, s60, 0x10000
	v_mov_b32_e32 v199, v1
	global_load_lds_dwordx4 v198, s[80:81]
	s_add_i32 m0, s60, 0x12000
	s_add_u32 s8, s80, 0x20000
	global_load_lds_dwordx4 v202, s[80:81]
	s_addc_u32 s9, s81, 0
	s_add_i32 m0, s60, 0x14000
	v_mov_b32_e32 v203, v1
	global_load_lds_dwordx4 v198, s[8:9]
	s_add_i32 m0, s60, 0x16000
	s_add_u32 s78, s46, s2
	s_addc_u32 s79, s47, s3
	s_add_u32 s78, s78, s32
	s_addc_u32 s79, s79, 0
	s_add_i32 s61, s60, 0x2000
	global_load_lds_dwordx4 v202, s[8:9]
	s_mov_b32 m0, s60
	s_add_u32 s2, s78, 0x100000
	global_load_lds_dwordx4 v196, s[78:79]
	s_mov_b32 m0, s61
	s_addc_u32 s3, s79, 0
	s_add_i32 s62, s60, 0x4000
	global_load_lds_dwordx4 v200, s[78:79]
	s_mov_b32 m0, s62
	s_add_i32 s84, s60, 0x6000
	global_load_lds_dwordx4 v196, s[2:3]
	s_mov_b32 m0, s84
	v_mov_b32_e32 v197, v1
	global_load_lds_dwordx4 v200, s[2:3]
	v_mov_b32_e32 v201, v1
	s_cmp_eq_u32 s0, 1
	s_mov_b32 s35, s58
	v_lshl_add_u64 v[8:9], s[80:81], 0, v[198:199]
	v_lshl_add_u64 v[6:7], s[80:81], 0, v[202:203]
	v_lshl_add_u64 v[2:3], s[78:79], 0, v[196:197]
	s_cselect_b64 s[8:9], -1, 0
	s_cmp_lg_u32 s0, 1
	v_lshl_add_u64 v[4:5], s[78:79], 0, v[200:201]
	s_cbranch_scc1 .LBB0_546
	s_barrier

; template <class Epi, class Sched>
; __device__ __forceinline__ void gemm_phase(LAS unsigned char* lds, const Gemm g, const Sched& S, const Epi& E, int wv) {
;     ...
;         const bool has_next = S.next(ui + 1, nxt);
;         const char* nA = has_next ? (const char*)g.A + (size_t)nxt.pm * tstepA + (size_t)nxt.ak * 2 : cA; const char* nB = has_next ? (const char*)g.Bt + (size_t)nxt.pn * tstepB : cB;
;         for (int t = 0; t < nt; t += 2) {
;             const bool last = (t == nt - 2);
;             const char* a1 = cA + (size_t)(t + 1) * kstep;
;             const char* a2 = last ? nA : cA + (size_t)(t + 2) * kstep; const char* b2 = last ? nB : cB + (size_t)(t + 2) * kstep;
.LBB0_549:
	s_mov_b32 s16, 0
	s_mov_b32 s17, 1
	s_cmp_eq_u32 s4, 1
	s_cselect_b32 s16, 4, s16
	s_cselect_b32 s17, 5, s17
	s_cmp_eq_u32 s4, 3
	s_cselect_b32 s16, -2, s16
	s_cselect_b32 s17, -1, s17
	s_add_i32 s91, s91, 1
	s_mul_i32 s0, s91, s87
	s_mul_hi_u32 s1, s91, s15
	s_add_i32 s1, s1, s0
	s_mul_i32 s0, s91, s15
	s_add_u32 s74, s0, s14
	s_addc_u32 s75, s1, s88
	v_mov_b64_e32 v[2:3], s[22:23]
	v_cmp_ge_i64_e32 vcc, s[74:75], v[2:3]
	v_cmp_lt_i64_e64 s[2:3], s[74:75], v[2:3]
	s_cbranch_vccnz .LBB0_555
	s_ashr_i32 s0, s74, 31
	s_lshr_b32 s0, s0, 29
	s_add_i32 s0, s74, s0
	s_and_b32 s1, s0, -8
	s_sub_i32 s1, s74, s1
	s_cmp_gt_i32 s1, -1
	s_mov_b64 s[70:71], -1
	s_cbranch_scc0 .LBB0_552
	s_lshl_b32 s5, s1, s89
	s_mov_b64 s[70:71], 0

; #define PG8_STAGE(bufoff, gbase, voff) do { _Pragma("unroll") for (int _i = 0; _i < 2; ++_i) \
;         __builtin_amdgcn_global_load_lds((const unsigned*)((const char*)(gbase) + (voff)[_i]), (LAS unsigned*)(lds + (bufoff) + ldsw + _i * 8192), 16, 0, 0); } while (0)
; #define PG8_LDA(dst, b, h) do { _Pragma("unroll") for (int m = 0; m < 4; ++m) _Pragma("unroll") for (int k = 0; k < 2; ++k) dst[m][k] = *(const LAS bf16x8*)(lds + PG8_SA(b, h) + aoff + m * 2048 + k * 1024); } while (0)
; #define PG8_LDB(dst, b, h) do { _Pragma("unroll") for (int n = 0; n < 2; ++n) _Pragma("unroll") for (int k = 0; k < 2; ++k) dst[n][k] = *(const LAS bf16x8*)(lds + PG8_SB(b, h) + boff + n * 2048 + k * 1024); } while (0)
; #define PG8_MMA(ai, bj, At, Bt) do { __builtin_amdgcn_s_setprio(1); _Pragma("unroll") for (int m = 0; m < 4; ++m) _Pragma("unroll") for (int n = 0; n < 2; ++n) _Pragma("unroll") for (int k = 0; k < 2; ++k) \
;         acc[ai][bj][m][n] = __builtin_amdgcn_mfma_f32_16x16x32_bf16(Bt[n][k], At[m][k], acc[ai][bj][m][n], 0, 0, 0); __builtin_amdgcn_s_setprio(0); } while (0)
; #define PG8_WAIT_V(n) asm volatile("s_waitcnt vmcnt(" #n ")" ::: "memory")
; #define PG8_WAIT_L(n) asm volatile("s_waitcnt lgkmcnt(" #n ")" ::: "memory")
; #define PG8_BAR __builtin_amdgcn_s_barrier()
; #define PG8_SCHED __builtin_amdgcn_sched_barrier(0)
; template <class Epi, class Sched>
; __device__ __forceinline__ void gemm_phase(LAS unsigned char* lds, const Gemm g, const Sched& S, const Epi& E, int wv) {
;     ...
;         const char* nA = has_next ? (const char*)g.A + (size_t)nxt.pm * tstepA + (size_t)nxt.ak * 2 : cA; const char* nB = has_next ? (const char*)g.Bt + (size_t)nxt.pn * tstepB : cB;
;         for (int t = 0; t < nt; t += 2) {
;             const bool last = (t == nt - 2);
;             const char* a1 = cA + (size_t)(t + 1) * kstep;
;             const char* a2 = last ? nA : cA + (size_t)(t + 2) * kstep; const char* b2 = last ? nB : cB + (size_t)(t + 2) * kstep;
;             const char* a3 = a2 + kstep; const char* b3 = b2 + kstep;
;             PG8_LDB(B0, 0, 0); PG8_LDB(B1, 0, 1); PG8_SCHED; PG8_LDA(At, 0, 0); PG8_STAGE(PG8_SA(1, 1), a1 + hstepA, voffA);
;             PG8_WAIT_V(8); PG8_WAIT_L(0); PG8_BAR; PG8_MMA(0, 0, At, B0); PG8_MMA(0, 1, At, B1); PG8_BAR; PG8_SCHED;
.LBB0_555:
	s_ashr_i32 s73, s72, 31
	s_lshl_b64 s[0:1], s[72:73], 21
	s_add_u32 s74, s46, s0
	s_addc_u32 s75, s47, s1
	s_cmp_gt_u32 s70, 1
	s_cselect_b32 s32, 0x200, 0
	s_add_u32 s74, s74, s32
	s_addc_u32 s75, s75, 0
	s_and_b64 s[0:1], s[2:3], exec
	s_cselect_b32 s5, s75, s79
	s_cselect_b32 s7, s74, s78
	s_ashr_i32 s71, s70, 31
	s_lshl_b64 s[0:1], s[70:71], 18
	s_add_u32 s76, s48, s0
	s_addc_u32 s77, s49, s1
	s_add_u32 s76, s76, s32
	s_addc_u32 s77, s77, 0
	s_and_b64 s[0:1], s[2:3], exec
	s_cselect_b32 s10, s77, s81
	s_cselect_b32 s11, s76, s80
	s_add_u32 s78, s78, 0x100080
	s_addc_u32 s79, s79, 0
	s_add_u32 s21, s80, 0x100
	v_mov_b32_e32 v2, 0
	s_addc_u32 s31, s81, 0
	s_mov_b32 s34, -2
	v_mov_b32_e32 v3, v2
	v_mov_b32_e32 v4, v2
	v_mov_b32_e32 v5, v2
	v_mov_b32_e32 v6, v2
	v_mov_b32_e32 v7, v2
	v_mov_b32_e32 v8, v2
	v_mov_b32_e32 v9, v2
	v_mov_b32_e32 v10, v2
	v_mov_b32_e32 v11, v2
	v_mov_b32_e32 v12, v2
	v_mov_b32_e32 v13, v2
	v_mov_b32_e32 v14, v2
	v_mov_b32_e32 v15, v2
	v_mov_b32_e32 v16, v2
	v_mov_b32_e32 v17, v2
	v_mov_b32_e32 v18, v2
	v_mov_b32_e32 v19, v2
	v_mov_b32_e32 v20, v2
	v_mov_b32_e32 v21, v2
	v_mov_b32_e32 v22, v2
	v_mov_b32_e32 v23, v2
	v_mov_b32_e32 v24, v2
	v_mov_b32_e32 v25, v2
	v_mov_b32_e32 v26, v2
	v_mov_b32_e32 v27, v2
	v_mov_b32_e32 v28, v2
	v_mov_b32_e32 v29, v2
	v_mov_b32_e32 v30, v2
	v_mov_b32_e32 v31, v2
	v_mov_b32_e32 v32, v2
	v_mov_b32_e32 v33, v2
	v_mov_b32_e32 v66, v2
	v_mov_b32_e32 v67, v2
	v_mov_b32_e32 v68, v2
	v_mov_b32_e32 v69, v2
	v_mov_b32_e32 v70, v2
	v_mov_b32_e32 v71, v2
	v_mov_b32_e32 v72, v2
	v_mov_b32_e32 v73, v2
	v_mov_b32_e32 v74, v2
	v_mov_b32_e32 v75, v2
	v_mov_b32_e32 v76, v2
	v_mov_b32_e32 v77, v2
	v_mov_b32_e32 v78, v2
	v_mov_b32_e32 v79, v2
	v_mov_b32_e32 v80, v2
	v_mov_b32_e32 v81, v2
	v_mov_b32_e32 v82, v2
	v_mov_b32_e32 v83, v2
	v_mov_b32_e32 v84, v2
	v_mov_b32_e32 v85, v2
	v_mov_b32_e32 v86, v2
	v_mov_b32_e32 v87, v2
	v_mov_b32_e32 v88, v2
	v_mov_b32_e32 v89, v2
	v_mov_b32_e32 v90, v2
	v_mov_b32_e32 v91, v2
	v_mov_b32_e32 v92, v2
	v_mov_b32_e32 v93, v2
	v_mov_b32_e32 v94, v2
	v_mov_b32_e32 v95, v2
	v_mov_b32_e32 v96, v2
	v_mov_b32_e32 v97, v2
	v_mov_b32_e32 v34, v2
	v_mov_b32_e32 v35, v2
	v_mov_b32_e32 v36, v2
	v_mov_b32_e32 v37, v2
	v_mov_b32_e32 v38, v2
	v_mov_b32_e32 v39, v2
	v_mov_b32_e32 v40, v2
	v_mov_b32_e32 v41, v2
	v_mov_b32_e32 v42, v2
	v_mov_b32_e32 v43, v2
	v_mov_b32_e32 v44, v2
	v_mov_b32_e32 v45, v2
	v_mov_b32_e32 v46, v2
	v_mov_b32_e32 v47, v2
	v_mov_b32_e32 v48, v2
	v_mov_b32_e32 v49, v2
	v_mov_b32_e32 v50, v2
	v_mov_b32_e32 v51, v2
	v_mov_b32_e32 v52, v2
	v_mov_b32_e32 v53, v2
	v_mov_b32_e32 v54, v2
	v_mov_b32_e32 v55, v2
	v_mov_b32_e32 v56, v2
	v_mov_b32_e32 v57, v2
	v_mov_b32_e32 v58, v2
	v_mov_b32_e32 v59, v2
	v_mov_b32_e32 v60, v2
	v_mov_b32_e32 v61, v2
	v_mov_b32_e32 v62, v2
	v_mov_b32_e32 v63, v2
	v_mov_b32_e32 v64, v2
	v_mov_b32_e32 v65, v2
	v_mov_b32_e32 v98, v2
	v_mov_b32_e32 v99, v2
	v_mov_b32_e32 v100, v2
	v_mov_b32_e32 v101, v2
	v_mov_b32_e32 v102, v2
	v_mov_b32_e32 v103, v2
	v_mov_b32_e32 v104, v2
	v_mov_b32_e32 v105, v2
	v_mov_b32_e32 v106, v2
	v_mov_b32_e32 v107, v2
	v_mov_b32_e32 v108, v2
	v_mov_b32_e32 v109, v2
	v_mov_b32_e32 v110, v2
	v_mov_b32_e32 v111, v2
	v_mov_b32_e32 v112, v2
	v_mov_b32_e32 v113, v2
	v_mov_b32_e32 v122, v2
	v_mov_b32_e32 v123, v2
	v_mov_b32_e32 v124, v2
	v_mov_b32_e32 v125, v2
	v_mov_b32_e32 v126, v2
	v_mov_b32_e32 v127, v2
	v_mov_b32_e32 v128, v2
	v_mov_b32_e32 v129, v2
	v_mov_b32_e32 v138, v2
	v_mov_b32_e32 v139, v2
	v_mov_b32_e32 v140, v2
	v_mov_b32_e32 v141, v2
	v_mov_b32_e32 v142, v2
	v_mov_b32_e32 v143, v2
	v_mov_b32_e32 v144, v2
	v_mov_b32_e32 v145, v2
.LBB0_556:
	s_add_u32 s0, s78, 0xfff00080
	s_addc_u32 s1, s79, -1
	s_add_i32 s20, 0, 0x10000
	s_cmp_eq_u32 s34, s16
	s_cselect_b32 s83, s5, s1
	s_cselect_b32 s82, s7, s0
	v_add_u32_e32 v0, s20, v231
	s_cselect_b32 s81, s10, s31
	s_cselect_b32 s80, s11, s21
	s_add_i32 s26, 0, 0x14000
	ds_read_b128 v[114:117], v0
	ds_read_b128 v[118:121], v0 offset:1024
	ds_read_b128 v[130:133], v0 offset:2048
	ds_read_b128 v[134:137], v0 offset:3072
	v_add_u32_e32 v0, s26, v231
	ds_read_b128 v[146:149], v0
	ds_read_b128 v[150:153], v0 offset:1024
	ds_read_b128 v[154:157], v0 offset:2048
	ds_read_b128 v[158:161], v0 offset:3072
	v_lshl_add_u64 v[208:209], s[78:79], 0, v[204:205]
	s_add_i32 m0, s60, 0xc000
	ds_read_b128 v[162:165], v232
	ds_read_b128 v[166:169], v232 offset:1024
	ds_read_b128 v[170:173], v232 offset:2048
	ds_read_b128 v[174:177], v232 offset:3072
	ds_read_b128 v[178:181], v232 offset:4096
	ds_read_b128 v[182:185], v232 offset:5120
	ds_read_b128 v[186:189], v232 offset:6144
	ds_read_b128 v[190:193], v232 offset:7168
	global_load_lds_dwordx4 v[208:209], off
	v_lshl_add_u64 v[208:209], s[78:79], 0, v[206:207]
	s_add_i32 m0, s60, 0xe000
	s_nop 0
	global_load_lds_dwordx4 v[208:209], off
	s_waitcnt vmcnt(8)
	s_waitcnt lgkmcnt(0)
	s_barrier
; #define PG8_STAGE(bufoff, gbase, voff) do { _Pragma("unroll") for (int _i = 0; _i < 2; ++_i) \
;         __builtin_amdgcn_global_load_lds((const unsigned*)((const char*)(gbase) + (voff)[_i]), (LAS unsigned*)(lds + (bufoff) + ldsw + _i * 8192), 16, 0, 0); } while (0)
; #define PG8_LDA(dst, b, h) do { _Pragma("unroll") for (int m = 0; m < 4; ++m) _Pragma("unroll") for (int k = 0; k < 2; ++k) dst[m][k] = *(const LAS bf16x8*)(lds + PG8_SA(b, h) + aoff + m * 2048 + k * 1024); } while (0)
; #define PG8_MMA(ai, bj, At, Bt) do { __builtin_amdgcn_s_setprio(1); _Pragma("unroll") for (int m = 0; m < 4; ++m) _Pragma("unroll") for (int n = 0; n < 2; ++n) _Pragma("unroll") for (int k = 0; k < 2; ++k) \
;         acc[ai][bj][m][n] = __builtin_amdgcn_mfma_f32_16x16x32_bf16(Bt[n][k], At[m][k], acc[ai][bj][m][n], 0, 0, 0); __builtin_amdgcn_s_setprio(0); } while (0)
; #define PG8_WAIT_V(n) asm volatile("s_waitcnt vmcnt(" #n ")" ::: "memory")
; #define PG8_WAIT_L(n) asm volatile("s_waitcnt lgkmcnt(" #n ")" ::: "memory")
; #define PG8_BAR __builtin_amdgcn_s_barrier()
; #define PG8_SCHED __builtin_amdgcn_sched_barrier(0)
; template <class Epi, class Sched>
; __device__ __forceinline__ void gemm_phase(LAS unsigned char* lds, const Gemm g, const Sched& S, const Epi& E, int wv) {
;     ...
;             PG8_WAIT_V(8); PG8_WAIT_L(0); PG8_BAR; PG8_MMA(0, 0, At, B0); PG8_MMA(0, 1, At, B1); PG8_BAR; PG8_SCHED;
;             PG8_LDA(At, 0, 1); PG8_STAGE(PG8_SB(0, 0), b2, voffB); PG8_STAGE(PG8_SB(0, 1), b2 + hstepB, voffB); PG8_STAGE(PG8_SA(0, 0), a2, voffA);
;             PG8_WAIT_V(8); PG8_WAIT_L(0); PG8_BAR; PG8_MMA(1, 0, At, B0); PG8_MMA(1, 1, At, B1); PG8_BAR; PG8_SCHED;
	s_setprio 1
	v_mfma_f32_16x16x32_bf16 v[142:145], v[114:117], v[162:165], v[142:145]
	v_mfma_f32_16x16x32_bf16 v[138:141], v[130:133], v[162:165], v[138:141]
	v_mfma_f32_16x16x32_bf16 v[126:129], v[114:117], v[170:173], v[126:129]
	v_mfma_f32_16x16x32_bf16 v[122:125], v[130:133], v[170:173], v[122:125]
	v_mfma_f32_16x16x32_bf16 v[110:113], v[114:117], v[178:181], v[110:113]
	v_mfma_f32_16x16x32_bf16 v[106:109], v[130:133], v[178:181], v[106:109]
	v_mfma_f32_16x16x32_bf16 v[102:105], v[114:117], v[186:189], v[102:105]
	v_mfma_f32_16x16x32_bf16 v[98:101], v[130:133], v[186:189], v[98:101]
	v_mfma_f32_16x16x32_bf16 v[142:145], v[118:121], v[166:169], v[142:145]
	v_mfma_f32_16x16x32_bf16 v[138:141], v[134:137], v[166:169], v[138:141]
	v_mfma_f32_16x16x32_bf16 v[126:129], v[118:121], v[174:177], v[126:129]
	v_mfma_f32_16x16x32_bf16 v[122:125], v[134:137], v[174:177], v[122:125]
	v_mfma_f32_16x16x32_bf16 v[110:113], v[118:121], v[182:185], v[110:113]
	v_mfma_f32_16x16x32_bf16 v[106:109], v[134:137], v[182:185], v[106:109]
	v_mfma_f32_16x16x32_bf16 v[102:105], v[118:121], v[190:193], v[102:105]
	v_mfma_f32_16x16x32_bf16 v[98:101], v[134:137], v[190:193], v[98:101]
	v_mfma_f32_16x16x32_bf16 v[62:65], v[146:149], v[162:165], v[62:65]
	v_mfma_f32_16x16x32_bf16 v[58:61], v[154:157], v[162:165], v[58:61]
	v_mfma_f32_16x16x32_bf16 v[54:57], v[146:149], v[170:173], v[54:57]
	v_mfma_f32_16x16x32_bf16 v[50:53], v[154:157], v[170:173], v[50:53]
	v_mfma_f32_16x16x32_bf16 v[46:49], v[146:149], v[178:181], v[46:49]
	v_mfma_f32_16x16x32_bf16 v[42:45], v[154:157], v[178:181], v[42:45]
	v_mfma_f32_16x16x32_bf16 v[38:41], v[146:149], v[186:189], v[38:41]
	v_mfma_f32_16x16x32_bf16 v[34:37], v[154:157], v[186:189], v[34:37]
	v_mfma_f32_16x16x32_bf16 v[62:65], v[150:153], v[166:169], v[62:65]
	v_mfma_f32_16x16x32_bf16 v[58:61], v[158:161], v[166:169], v[58:61]
	v_mfma_f32_16x16x32_bf16 v[54:57], v[150:153], v[174:177], v[54:57]
	v_mfma_f32_16x16x32_bf16 v[50:53], v[158:161], v[174:177], v[50:53]
	v_mfma_f32_16x16x32_bf16 v[46:49], v[150:153], v[182:185], v[46:49]
	v_mfma_f32_16x16x32_bf16 v[42:45], v[158:161], v[182:185], v[42:45]
	v_mfma_f32_16x16x32_bf16 v[38:41], v[150:153], v[190:193], v[38:41]
	v_mfma_f32_16x16x32_bf16 v[34:37], v[158:161], v[190:193], v[34:37]
	s_setprio 0
	s_barrier
	s_add_i32 s0, s20, s50
	v_lshl_add_u64 v[208:209], s[80:81], 0, v[198:199]
	s_mov_b32 m0, s0
	ds_read_b128 v[162:165], v232 offset:16384
	ds_read_b128 v[166:169], v232 offset:17408
	ds_read_b128 v[170:173], v232 offset:18432
	ds_read_b128 v[174:177], v232 offset:19456
	ds_read_b128 v[178:181], v232 offset:20480
	ds_read_b128 v[182:185], v232 offset:21504
	ds_read_b128 v[186:189], v232 offset:22528
	ds_read_b128 v[190:193], v232 offset:23552
	global_load_lds_dwordx4 v[208:209], off
	s_add_i32 m0, s0, 0x2000
	s_add_u32 s0, s80, 0x20000
	v_lshl_add_u64 v[210:211], s[80:81], 0, v[202:203]
	s_addc_u32 s1, s81, 0
	s_add_i32 s20, s26, s50
	global_load_lds_dwordx4 v[210:211], off
	v_lshl_add_u64 v[212:213], s[0:1], 0, v[198:199]
	s_mov_b32 m0, s20
	v_lshl_add_u64 v[214:215], s[82:83], 0, v[200:201]
	global_load_lds_dwordx4 v[212:213], off
	v_lshl_add_u64 v[212:213], s[0:1], 0, v[202:203]
	s_add_i32 m0, s20, 0x2000
	s_nop 0
	global_load_lds_dwordx4 v[212:213], off
	v_lshl_add_u64 v[212:213], s[82:83], 0, v[196:197]
	s_mov_b32 m0, s60
	s_nop 0
	global_load_lds_dwordx4 v[212:213], off
	s_mov_b32 m0, s61
	s_nop 0
	global_load_lds_dwordx4 v[214:215], off
	s_waitcnt vmcnt(8)
	s_waitcnt lgkmcnt(0)
	s_barrier
	s_setprio 1
	v_mfma_f32_16x16x32_bf16 v[94:97], v[114:117], v[162:165], v[94:97]
	v_mfma_f32_16x16x32_bf16 v[90:93], v[130:133], v[162:165], v[90:93]
	v_mfma_f32_16x16x32_bf16 v[86:89], v[114:117], v[170:173], v[86:89]
	v_mfma_f32_16x16x32_bf16 v[82:85], v[130:133], v[170:173], v[82:85]
	v_mfma_f32_16x16x32_bf16 v[78:81], v[114:117], v[178:181], v[78:81]
	v_mfma_f32_16x16x32_bf16 v[74:77], v[130:133], v[178:181], v[74:77]
	v_mfma_f32_16x16x32_bf16 v[70:73], v[114:117], v[186:189], v[70:73]
	v_mfma_f32_16x16x32_bf16 v[66:69], v[130:133], v[186:189], v[66:69]
	v_mfma_f32_16x16x32_bf16 v[94:97], v[118:121], v[166:169], v[94:97]
	v_mfma_f32_16x16x32_bf16 v[90:93], v[134:137], v[166:169], v[90:93]
	v_mfma_f32_16x16x32_bf16 v[86:89], v[118:121], v[174:177], v[86:89]
	v_mfma_f32_16x16x32_bf16 v[82:85], v[134:137], v[174:177], v[82:85]
	v_mfma_f32_16x16x32_bf16 v[78:81], v[118:121], v[182:185], v[78:81]
	v_mfma_f32_16x16x32_bf16 v[74:77], v[134:137], v[182:185], v[74:77]
	v_mfma_f32_16x16x32_bf16 v[70:73], v[118:121], v[190:193], v[70:73]
	v_mfma_f32_16x16x32_bf16 v[66:69], v[134:137], v[190:193], v[66:69]
	v_mfma_f32_16x16x32_bf16 v[30:33], v[146:149], v[162:165], v[30:33]
	v_mfma_f32_16x16x32_bf16 v[26:29], v[154:157], v[162:165], v[26:29]
	v_mfma_f32_16x16x32_bf16 v[22:25], v[146:149], v[170:173], v[22:25]
	v_mfma_f32_16x16x32_bf16 v[18:21], v[154:157], v[170:173], v[18:21]
	v_mfma_f32_16x16x32_bf16 v[14:17], v[146:149], v[178:181], v[14:17]
	v_mfma_f32_16x16x32_bf16 v[10:13], v[154:157], v[178:181], v[10:13]
	v_mfma_f32_16x16x32_bf16 v[6:9], v[146:149], v[186:189], v[6:9]
	v_mfma_f32_16x16x32_bf16 v[2:5], v[154:157], v[186:189], v[2:5]
	v_mfma_f32_16x16x32_bf16 v[30:33], v[150:153], v[166:169], v[30:33]
	v_mfma_f32_16x16x32_bf16 v[26:29], v[158:161], v[166:169], v[26:29]
	v_mfma_f32_16x16x32_bf16 v[22:25], v[150:153], v[174:177], v[22:25]
	v_mfma_f32_16x16x32_bf16 v[18:21], v[158:161], v[174:177], v[18:21]
	v_mfma_f32_16x16x32_bf16 v[14:17], v[150:153], v[182:185], v[14:17]
	v_mfma_f32_16x16x32_bf16 v[10:13], v[158:161], v[182:185], v[10:13]
	v_mfma_f32_16x16x32_bf16 v[6:9], v[150:153], v[190:193], v[6:9]
	v_mfma_f32_16x16x32_bf16 v[2:5], v[158:161], v[190:193], v[2:5]
	s_setprio 0
	s_barrier
; #define PG8_STAGE(bufoff, gbase, voff) do { _Pragma("unroll") for (int _i = 0; _i < 2; ++_i) \
;         __builtin_amdgcn_global_load_lds((const unsigned*)((const char*)(gbase) + (voff)[_i]), (LAS unsigned*)(lds + (bufoff) + ldsw + _i * 8192), 16, 0, 0); } while (0)
; #define PG8_LDA(dst, b, h) do { _Pragma("unroll") for (int m = 0; m < 4; ++m) _Pragma("unroll") for (int k = 0; k < 2; ++k) dst[m][k] = *(const LAS bf16x8*)(lds + PG8_SA(b, h) + aoff + m * 2048 + k * 1024); } while (0)
; #define PG8_LDB(dst, b, h) do { _Pragma("unroll") for (int n = 0; n < 2; ++n) _Pragma("unroll") for (int k = 0; k < 2; ++k) dst[n][k] = *(const LAS bf16x8*)(lds + PG8_SB(b, h) + boff + n * 2048 + k * 1024); } while (0)
; #define PG8_MMA(ai, bj, At, Bt) do { __builtin_amdgcn_s_setprio(1); _Pragma("unroll") for (int m = 0; m < 4; ++m) _Pragma("unroll") for (int n = 0; n < 2; ++n) _Pragma("unroll") for (int k = 0; k < 2; ++k) \
;         acc[ai][bj][m][n] = __builtin_amdgcn_mfma_f32_16x16x32_bf16(Bt[n][k], At[m][k], acc[ai][bj][m][n], 0, 0, 0); __builtin_amdgcn_s_setprio(0); } while (0)
; #define PG8_WAIT_V(n) asm volatile("s_waitcnt vmcnt(" #n ")" ::: "memory")
; #define PG8_WAIT_L(n) asm volatile("s_waitcnt lgkmcnt(" #n ")" ::: "memory")
; #define PG8_BAR __builtin_amdgcn_s_barrier()
; #define PG8_SCHED __builtin_amdgcn_sched_barrier(0)
; template <class Epi, class Sched>
; __device__ __forceinline__ void gemm_phase(LAS unsigned char* lds, const Gemm g, const Sched& S, const Epi& E, int wv) {
;     ...
;             PG8_LDB(B0, 1, 0); PG8_LDB(B1, 1, 1); PG8_SCHED; PG8_LDA(At, 1, 0); PG8_STAGE(PG8_SA(0, 1), a2 + hstepA, voffA);
;             PG8_WAIT_V(8); PG8_WAIT_L(0); PG8_BAR; PG8_MMA(0, 0, At, B0); PG8_MMA(0, 1, At, B1); PG8_BAR; PG8_SCHED;
	s_add_i32 s20, 0, 0x18000
	v_add_u32_e32 v0, s20, v231
	s_add_i32 s26, 0, 0x1c000
	ds_read_b128 v[114:117], v0
	ds_read_b128 v[118:121], v0 offset:1024
	ds_read_b128 v[130:133], v0 offset:2048
	ds_read_b128 v[134:137], v0 offset:3072
	v_add_u32_e32 v0, s26, v231
	ds_read_b128 v[146:149], v0
	ds_read_b128 v[150:153], v0 offset:1024
	ds_read_b128 v[154:157], v0 offset:2048
	ds_read_b128 v[158:161], v0 offset:3072
	s_add_u32 s0, s82, 0x100000
	s_addc_u32 s1, s83, 0
	s_mov_b32 m0, s62
	v_lshl_add_u64 v[216:217], s[0:1], 0, v[196:197]
	ds_read_b128 v[162:165], v232 offset:32768
	ds_read_b128 v[166:169], v232 offset:33792
	ds_read_b128 v[170:173], v232 offset:34816
	ds_read_b128 v[174:177], v232 offset:35840
	ds_read_b128 v[178:181], v232 offset:36864
	ds_read_b128 v[182:185], v232 offset:37888
	ds_read_b128 v[186:189], v232 offset:38912
	ds_read_b128 v[190:193], v232 offset:39936
	global_load_lds_dwordx4 v[216:217], off
	v_lshl_add_u64 v[216:217], s[0:1], 0, v[200:201]
	s_mov_b32 m0, s84
	s_nop 0
	global_load_lds_dwordx4 v[216:217], off
	s_waitcnt vmcnt(8)
	s_waitcnt lgkmcnt(0)
	s_barrier
	s_setprio 1
	v_mfma_f32_16x16x32_bf16 v[142:145], v[114:117], v[162:165], v[142:145]
	v_mfma_f32_16x16x32_bf16 v[138:141], v[130:133], v[162:165], v[138:141]
	v_mfma_f32_16x16x32_bf16 v[126:129], v[114:117], v[170:173], v[126:129]
	v_mfma_f32_16x16x32_bf16 v[122:125], v[130:133], v[170:173], v[122:125]
	v_mfma_f32_16x16x32_bf16 v[110:113], v[114:117], v[178:181], v[110:113]
	v_mfma_f32_16x16x32_bf16 v[106:109], v[130:133], v[178:181], v[106:109]
	v_mfma_f32_16x16x32_bf16 v[102:105], v[114:117], v[186:189], v[102:105]
	v_mfma_f32_16x16x32_bf16 v[98:101], v[130:133], v[186:189], v[98:101]
	v_mfma_f32_16x16x32_bf16 v[142:145], v[118:121], v[166:169], v[142:145]
	v_mfma_f32_16x16x32_bf16 v[138:141], v[134:137], v[166:169], v[138:141]
	v_mfma_f32_16x16x32_bf16 v[126:129], v[118:121], v[174:177], v[126:129]
	v_mfma_f32_16x16x32_bf16 v[122:125], v[134:137], v[174:177], v[122:125]
	v_mfma_f32_16x16x32_bf16 v[110:113], v[118:121], v[182:185], v[110:113]
	v_mfma_f32_16x16x32_bf16 v[106:109], v[134:137], v[182:185], v[106:109]
	v_mfma_f32_16x16x32_bf16 v[102:105], v[118:121], v[190:193], v[102:105]
	v_mfma_f32_16x16x32_bf16 v[98:101], v[134:137], v[190:193], v[98:101]
	v_mfma_f32_16x16x32_bf16 v[62:65], v[146:149], v[162:165], v[62:65]
	v_mfma_f32_16x16x32_bf16 v[58:61], v[154:157], v[162:165], v[58:61]
	v_mfma_f32_16x16x32_bf16 v[54:57], v[146:149], v[170:173], v[54:57]
	v_mfma_f32_16x16x32_bf16 v[50:53], v[154:157], v[170:173], v[50:53]
	v_mfma_f32_16x16x32_bf16 v[46:49], v[146:149], v[178:181], v[46:49]
	v_mfma_f32_16x16x32_bf16 v[42:45], v[154:157], v[178:181], v[42:45]
	v_mfma_f32_16x16x32_bf16 v[38:41], v[146:149], v[186:189], v[38:41]
	v_mfma_f32_16x16x32_bf16 v[34:37], v[154:157], v[186:189], v[34:37]
	v_mfma_f32_16x16x32_bf16 v[62:65], v[150:153], v[166:169], v[62:65]
	v_mfma_f32_16x16x32_bf16 v[58:61], v[158:161], v[166:169], v[58:61]
	v_mfma_f32_16x16x32_bf16 v[54:57], v[150:153], v[174:177], v[54:57]
	v_mfma_f32_16x16x32_bf16 v[50:53], v[158:161], v[174:177], v[50:53]
	v_mfma_f32_16x16x32_bf16 v[46:49], v[150:153], v[182:185], v[46:49]
	v_mfma_f32_16x16x32_bf16 v[42:45], v[158:161], v[182:185], v[42:45]
	v_mfma_f32_16x16x32_bf16 v[38:41], v[150:153], v[190:193], v[38:41]
	v_mfma_f32_16x16x32_bf16 v[34:37], v[158:161], v[190:193], v[34:37]
	s_setprio 0
	s_barrier
; #define PG8_STAGE(bufoff, gbase, voff) do { _Pragma("unroll") for (int _i = 0; _i < 2; ++_i) \
;         __builtin_amdgcn_global_load_lds((const unsigned*)((const char*)(gbase) + (voff)[_i]), (LAS unsigned*)(lds + (bufoff) + ldsw + _i * 8192), 16, 0, 0); } while (0)
; #define PG8_LDA(dst, b, h) do { _Pragma("unroll") for (int m = 0; m < 4; ++m) _Pragma("unroll") for (int k = 0; k < 2; ++k) dst[m][k] = *(const LAS bf16x8*)(lds + PG8_SA(b, h) + aoff + m * 2048 + k * 1024); } while (0)
; #define PG8_MMA(ai, bj, At, Bt) do { __builtin_amdgcn_s_setprio(1); _Pragma("unroll") for (int m = 0; m < 4; ++m) _Pragma("unroll") for (int n = 0; n < 2; ++n) _Pragma("unroll") for (int k = 0; k < 2; ++k) \
;         acc[ai][bj][m][n] = __builtin_amdgcn_mfma_f32_16x16x32_bf16(Bt[n][k], At[m][k], acc[ai][bj][m][n], 0, 0, 0); __builtin_amdgcn_s_setprio(0); } while (0)
; #define PG8_WAIT_V(n) asm volatile("s_waitcnt vmcnt(" #n ")" ::: "memory")
; #define PG8_WAIT_L(n) asm volatile("s_waitcnt lgkmcnt(" #n ")" ::: "memory")
; #define PG8_BAR __builtin_amdgcn_s_barrier()
; #define PG8_SCHED __builtin_amdgcn_sched_barrier(0)
; template <class Epi, class Sched>
; __device__ __forceinline__ void gemm_phase(LAS unsigned char* lds, const Gemm g, const Sched& S, const Epi& E, int wv) {
;     ...
;             PG8_LDA(At, 1, 1); PG8_STAGE(PG8_SB(1, 0), b3, voffB); PG8_STAGE(PG8_SB(1, 1), b3 + hstepB, voffB); PG8_STAGE(PG8_SA(1, 0), a3, voffA);
;             PG8_WAIT_V(8); PG8_WAIT_L(0); PG8_BAR; PG8_MMA(1, 0, At, B0); PG8_MMA(1, 1, At, B1); PG8_BAR; PG8_SCHED;
;         }
	s_add_i32 s0, s20, s50
	v_lshl_add_u64 v[208:209], v[208:209], 0, s[24:25]
	s_mov_b32 m0, s0
	ds_read_b128 v[162:165], v232 offset:49152
	ds_read_b128 v[166:169], v232 offset:50176
	ds_read_b128 v[170:173], v232 offset:51200
	ds_read_b128 v[174:177], v232 offset:52224
	ds_read_b128 v[178:181], v232 offset:53248
	ds_read_b128 v[182:185], v232 offset:54272
	ds_read_b128 v[186:189], v232 offset:55296
	ds_read_b128 v[190:193], v232 offset:56320
	global_load_lds_dwordx4 v[208:209], off
	s_add_i32 m0, s0, 0x2000
	s_add_u32 s0, s80, 0x20080
	v_lshl_add_u64 v[208:209], v[210:211], 0, s[24:25]
	s_addc_u32 s1, s81, 0
	s_add_i32 s20, s26, s50
	global_load_lds_dwordx4 v[208:209], off
	v_lshl_add_u64 v[208:209], s[0:1], 0, v[198:199]
	s_mov_b32 m0, s20
	s_nop 0
	global_load_lds_dwordx4 v[208:209], off
	v_lshl_add_u64 v[208:209], s[0:1], 0, v[202:203]
	s_add_i32 m0, s20, 0x2000
	s_nop 0
	global_load_lds_dwordx4 v[208:209], off
	v_lshl_add_u64 v[208:209], v[212:213], 0, s[24:25]
	s_mov_b32 m0, s85
	s_nop 0
	global_load_lds_dwordx4 v[208:209], off
	v_lshl_add_u64 v[208:209], v[214:215], 0, s[24:25]
	s_mov_b32 m0, s86
	s_nop 0
	global_load_lds_dwordx4 v[208:209], off
	s_waitcnt vmcnt(8)
	s_waitcnt lgkmcnt(0)
	s_barrier
	s_setprio 1
	v_mfma_f32_16x16x32_bf16 v[94:97], v[114:117], v[162:165], v[94:97]
	v_mfma_f32_16x16x32_bf16 v[90:93], v[130:133], v[162:165], v[90:93]
	v_mfma_f32_16x16x32_bf16 v[86:89], v[114:117], v[170:173], v[86:89]
	v_mfma_f32_16x16x32_bf16 v[82:85], v[130:133], v[170:173], v[82:85]
	v_mfma_f32_16x16x32_bf16 v[78:81], v[114:117], v[178:181], v[78:81]
	v_mfma_f32_16x16x32_bf16 v[74:77], v[130:133], v[178:181], v[74:77]
	v_mfma_f32_16x16x32_bf16 v[70:73], v[114:117], v[186:189], v[70:73]
	v_mfma_f32_16x16x32_bf16 v[66:69], v[130:133], v[186:189], v[66:69]
	v_mfma_f32_16x16x32_bf16 v[94:97], v[118:121], v[166:169], v[94:97]
	v_mfma_f32_16x16x32_bf16 v[90:93], v[134:137], v[166:169], v[90:93]
	v_mfma_f32_16x16x32_bf16 v[86:89], v[118:121], v[174:177], v[86:89]
	v_mfma_f32_16x16x32_bf16 v[82:85], v[134:137], v[174:177], v[82:85]
	v_mfma_f32_16x16x32_bf16 v[78:81], v[118:121], v[182:185], v[78:81]
	v_mfma_f32_16x16x32_bf16 v[74:77], v[134:137], v[182:185], v[74:77]
	v_mfma_f32_16x16x32_bf16 v[70:73], v[118:121], v[190:193], v[70:73]
	v_mfma_f32_16x16x32_bf16 v[66:69], v[134:137], v[190:193], v[66:69]
	v_mfma_f32_16x16x32_bf16 v[30:33], v[146:149], v[162:165], v[30:33]
	v_mfma_f32_16x16x32_bf16 v[26:29], v[154:157], v[162:165], v[26:29]
	v_mfma_f32_16x16x32_bf16 v[22:25], v[146:149], v[170:173], v[22:25]
	v_mfma_f32_16x16x32_bf16 v[18:21], v[154:157], v[170:173], v[18:21]
	v_mfma_f32_16x16x32_bf16 v[14:17], v[146:149], v[178:181], v[14:17]
	v_mfma_f32_16x16x32_bf16 v[10:13], v[154:157], v[178:181], v[10:13]
	v_mfma_f32_16x16x32_bf16 v[6:9], v[146:149], v[186:189], v[6:9]
	v_mfma_f32_16x16x32_bf16 v[2:5], v[154:157], v[186:189], v[2:5]
	v_mfma_f32_16x16x32_bf16 v[30:33], v[150:153], v[166:169], v[30:33]
	v_mfma_f32_16x16x32_bf16 v[26:29], v[158:161], v[166:169], v[26:29]
	v_mfma_f32_16x16x32_bf16 v[22:25], v[150:153], v[174:177], v[22:25]
	v_mfma_f32_16x16x32_bf16 v[18:21], v[158:161], v[174:177], v[18:21]
	v_mfma_f32_16x16x32_bf16 v[14:17], v[150:153], v[182:185], v[14:17]
	v_mfma_f32_16x16x32_bf16 v[10:13], v[158:161], v[182:185], v[10:13]
	v_mfma_f32_16x16x32_bf16 v[6:9], v[150:153], v[190:193], v[6:9]
	v_mfma_f32_16x16x32_bf16 v[2:5], v[158:161], v[190:193], v[2:5]
	s_setprio 0
	s_barrier
	s_add_i32 s34, s34, 2
	s_add_u32 s78, s78, 0x100
	s_addc_u32 s79, s79, 0
	s_add_u32 s21, s21, 0x100
	s_addc_u32 s31, s31, 0
	s_cmp_gt_i32 s34, s17
	s_cbranch_scc0 .LBB0_556
	s_and_b64 vcc, exec, s[68:69]
	s_cbranch_vccz .LBB0_559
	s_barrier

; template <class Epi, class Sched>
; __device__ __forceinline__ void gemm_phase(LAS unsigned char* lds, const Gemm g, const Sched& S, const Epi& E, int wv) {
;     ...
;         const bool has_next = S.next(ui + 1, nxt);
;         const char* nA = has_next ? (const char*)g.A + (size_t)nxt.pm * tstepA + (size_t)nxt.ak * 2 : cA; const char* nB = has_next ? (const char*)g.Bt + (size_t)nxt.pn * tstepB : cB;
;     ...
; #pragma unroll
;         for (int a = 0; a < 2; ++a)
; #pragma unroll
;             for (int b = 0; b < 2; ++b)
; #pragma unroll
;                 for (int m = 0; m < 4; ++m)
; #pragma unroll
;                     for (int n = 0; n < 2; ++n) acc[a][b][m][n] = (f32x4){0.f, 0.f, 0.f, 0.f};
;         cur = nxt; cA = nA; cB = nB; ++ui;
.LBB0_716:
	s_ashr_i32 s79, s78, 31
	s_lshl_b64 s[0:1], s[78:79], 19
	s_add_u32 s80, s46, s0
	s_addc_u32 s81, s47, s1
	s_and_b64 s[0:1], s[2:3], exec
	s_cselect_b32 s5, s81, s9
	s_cselect_b32 s7, s80, s8
	s_ashr_i32 s77, s76, 31
	s_lshl_b64 s[0:1], s[76:77], 19
	s_add_u32 s82, s57, s0
	s_addc_u32 s83, s33, s1
	s_and_b64 s[0:1], s[2:3], exec
	s_cselect_b32 s21, s83, s13
	s_cselect_b32 s22, s82, s12
	s_add_u32 s8, s8, 0x40080
	s_addc_u32 s9, s9, 0
	s_add_u32 s31, s12, 0x100
	v_mov_b32_e32 v2, 0
	s_addc_u32 s34, s13, 0
	s_mov_b32 s35, -2
	v_mov_b64_e32 v[2:3], 0
	v_mov_b64_e32 v[4:5], 0
	v_mov_b64_e32 v[6:7], 0
	v_mov_b64_e32 v[8:9], 0
	v_mov_b64_e32 v[10:11], 0
	v_mov_b64_e32 v[12:13], 0
	v_mov_b64_e32 v[14:15], 0
	v_mov_b64_e32 v[16:17], 0
	v_mov_b64_e32 v[18:19], 0
	v_mov_b64_e32 v[20:21], 0
	v_mov_b64_e32 v[22:23], 0
	v_mov_b64_e32 v[24:25], 0
	v_mov_b64_e32 v[26:27], 0
	v_mov_b64_e32 v[28:29], 0
	v_mov_b64_e32 v[30:31], 0
	v_mov_b64_e32 v[32:33], 0
	v_mov_b64_e32 v[34:35], 0
	v_mov_b64_e32 v[36:37], 0
	v_mov_b64_e32 v[38:39], 0
	v_mov_b64_e32 v[40:41], 0
	v_mov_b64_e32 v[42:43], 0
	v_mov_b64_e32 v[44:45], 0
	v_mov_b64_e32 v[46:47], 0
	v_mov_b64_e32 v[48:49], 0
	v_mov_b64_e32 v[50:51], 0
	v_mov_b64_e32 v[52:53], 0
	v_mov_b64_e32 v[54:55], 0
	v_mov_b64_e32 v[56:57], 0
	v_mov_b64_e32 v[58:59], 0
	v_mov_b64_e32 v[60:61], 0
	v_mov_b64_e32 v[62:63], 0
	v_mov_b64_e32 v[64:65], 0
	v_mov_b64_e32 v[66:67], 0
	v_mov_b64_e32 v[68:69], 0
	v_mov_b64_e32 v[70:71], 0
	v_mov_b64_e32 v[72:73], 0
	v_mov_b64_e32 v[74:75], 0
	v_mov_b64_e32 v[76:77], 0
	v_mov_b64_e32 v[78:79], 0
	v_mov_b64_e32 v[80:81], 0
	v_mov_b64_e32 v[82:83], 0
	v_mov_b64_e32 v[84:85], 0
	v_mov_b64_e32 v[86:87], 0
	v_mov_b64_e32 v[88:89], 0
	v_mov_b64_e32 v[90:91], 0
	v_mov_b64_e32 v[92:93], 0
	v_mov_b64_e32 v[94:95], 0
	v_mov_b64_e32 v[96:97], 0
	v_mov_b64_e32 v[98:99], 0
	v_mov_b64_e32 v[100:101], 0
	v_mov_b64_e32 v[102:103], 0
	v_mov_b64_e32 v[104:105], 0
	v_mov_b64_e32 v[106:107], 0
	v_mov_b64_e32 v[108:109], 0
	v_mov_b64_e32 v[110:111], 0
	v_mov_b64_e32 v[112:113], 0
	v_mov_b64_e32 v[114:115], 0
	v_mov_b64_e32 v[116:117], 0
	v_mov_b64_e32 v[118:119], 0
	v_mov_b64_e32 v[120:121], 0
	v_mov_b64_e32 v[122:123], 0
	v_mov_b64_e32 v[124:125], 0
	v_mov_b64_e32 v[126:127], 0
	v_mov_b64_e32 v[128:129], 0
